# GEMM K-loops: setprio 1 before the barrier, duplicate lgkmcnt(0) behind it dropped, closing barrier before setprio 0; attention trims
# speedup vs baseline: 1.0025x; 1.0021x over previous
; #define PG8_STAGE(bufoff, gbase, voff) do { _Pragma("unroll") for (int _i = 0; _i < 2; ++_i) \
;         __builtin_amdgcn_global_load_lds((const unsigned*)((const char*)(gbase) + (voff)[_i]), (PG8_LAS unsigned*)(lds + (bufoff) + ldsw + _i * 8192), 16, 0, 0); } while (0)
; #define PG8_LDA(dst, b, h) do { _Pragma("unroll") for (int m = 0; m < 4; ++m) _Pragma("unroll") for (int k = 0; k < 2; ++k) dst[m][k] = *(const PG8_LAS bf16x8*)(lds + PG8_SA(b, h) + aoff + m * 2048 + k * 1024); } while (0)
; #define PG8_LDB(dst, b, h) do { _Pragma("unroll") for (int n = 0; n < 2; ++n) _Pragma("unroll") for (int k = 0; k < 2; ++k) dst[n][k] = *(const PG8_LAS bf16x8*)(lds + PG8_SB(b, h) + boff + n * 2048 + k * 1024); } while (0)
; #define PG8_MMA(ai, bj, At, Bt) do { __builtin_amdgcn_s_setprio(1); _Pragma("unroll") for (int m = 0; m < 4; ++m) _Pragma("unroll") for (int n = 0; n < 2; ++n) _Pragma("unroll") for (int k = 0; k < 2; ++k) \
;         acc[ai][bj][m][n] = __builtin_amdgcn_mfma_f32_16x16x32_bf16(Bt[n][k], At[m][k], acc[ai][bj][m][n], 0, 0, 0); __builtin_amdgcn_s_setprio(0); } while (0)
; #define PG8_WAIT_V(n) asm volatile("s_waitcnt vmcnt(" #n ")" ::: "memory")
; #define PG8_WAIT_L(n) asm volatile("s_waitcnt lgkmcnt(" #n ")" ::: "memory")
; #define PG8_BAR __builtin_amdgcn_s_barrier()
; template <class Epi, class Sched, bool ALIGN_EPI = false, bool SP2 = false>
; __device__ __forceinline__ void gemm_phase(PG8_LAS unsigned char* lds, const Gemm g, const Sched& S, const Epi& E) {
;     ...
;         const bool has_next = S.next(ui + 1, nxt);
;         const char* nA = has_next ? (const char*)g.A + (size_t)nxt.pm * tstep : cA; const char* nB = has_next ? (const char*)g.Bt + (size_t)nxt.pn * tstep : cB;
;         for (int t = 0; t < nt; t += 2) {
;             const bool last = (t == nt - 2);
;             const char* a1 = cA + (size_t)(t + 1) * kstep;
;             const char* a2 = last ? nA : cA + (size_t)(t + 2) * kstep; const char* b2 = last ? nB : cB + (size_t)(t + 2) * kstep;
;             const char* a3 = a2 + kstep; const char* b3 = b2 + kstep;
;             if (last && has_next) S.a_ready(nxt);
;             if constexpr (SP2) {
;             PG8_LDB(B0, 0, 0); PG8_LDB(B1, 0, 1); PG8_SCHED; PG8_LDA(At, 0, 0); PG8_STAGE(PG8_SA(1, 1), a1 + hstep, voffA);
;             PG8_WAIT_V(8); PG8_WAIT_L(0); PG8_BAR; PG8_MMA(0, 0, At, B0); PG8_MMA(0, 1, At, B1); PG8_BAR; PG8_SCHED;
.LBB0_180:
	s_add_u32 s50, s44, 0xfffc0080
	s_addc_u32 s51, s45, -1
	s_add_i32 s72, 0, 0x10000
	s_cmp_eq_u32 s71, 12
	s_cselect_b32 vcc_hi, s0, s51
	s_cselect_b32 vcc_lo, s1, s50
	s_cselect_b32 s51, s4, s57
	s_cselect_b32 s50, s5, s39
	s_add_i32 s74, 0, 0x14000
	v_add_u32_e32 v88, s72, v208
	v_add_u32_e32 v116, s74, v208
	ds_read_b128 v[76:79], v88
	ds_read_b128 v[80:83], v88 offset:1024
	ds_read_b128 v[84:87], v88 offset:2048
	ds_read_b128 v[88:91], v88 offset:3072
	ds_read_b128 v[92:95], v116
	ds_read_b128 v[100:103], v116 offset:1024
	ds_read_b128 v[108:111], v116 offset:2048
	ds_read_b128 v[116:119], v116 offset:3072
	v_lshl_add_u64 v[186:187], s[44:45], 0, v[170:171]
	s_add_i32 m0, s53, 0xc000
	ds_read_b128 v[174:177], v218
	ds_read_b128 v[178:181], v218 offset:1024
	ds_read_b128 v[182:185], v218 offset:2048
	ds_read_b128 v[194:197], v218 offset:3072
	ds_read_b128 v[198:201], v218 offset:4096
	ds_read_b128 v[202:205], v218 offset:5120
	ds_read_b128 v[220:223], v218 offset:6144
	ds_read_b128 v[224:227], v218 offset:7168
	global_load_lds_dwordx4 v[186:187], off
	v_lshl_add_u64 v[186:187], s[44:45], 0, v[172:173]
	s_add_i32 m0, s53, 0xe000
	s_nop 0
	global_load_lds_dwordx4 v[186:187], off
	s_waitcnt vmcnt(8)
	s_waitcnt lgkmcnt(0)
	s_setprio 1
	s_barrier

; #define PG8_STAGE(bufoff, gbase, voff) do { _Pragma("unroll") for (int _i = 0; _i < 2; ++_i) \
;         __builtin_amdgcn_global_load_lds((const unsigned*)((const char*)(gbase) + (voff)[_i]), (PG8_LAS unsigned*)(lds + (bufoff) + ldsw + _i * 8192), 16, 0, 0); } while (0)
; #define PG8_LDA(dst, b, h) do { _Pragma("unroll") for (int m = 0; m < 4; ++m) _Pragma("unroll") for (int k = 0; k < 2; ++k) dst[m][k] = *(const PG8_LAS bf16x8*)(lds + PG8_SA(b, h) + aoff + m * 2048 + k * 1024); } while (0)
; #define PG8_MMA(ai, bj, At, Bt) do { __builtin_amdgcn_s_setprio(1); _Pragma("unroll") for (int m = 0; m < 4; ++m) _Pragma("unroll") for (int n = 0; n < 2; ++n) _Pragma("unroll") for (int k = 0; k < 2; ++k) \
;         acc[ai][bj][m][n] = __builtin_amdgcn_mfma_f32_16x16x32_bf16(Bt[n][k], At[m][k], acc[ai][bj][m][n], 0, 0, 0); __builtin_amdgcn_s_setprio(0); } while (0)
; #define PG8_WAIT_V(n) asm volatile("s_waitcnt vmcnt(" #n ")" ::: "memory")
; #define PG8_WAIT_L(n) asm volatile("s_waitcnt lgkmcnt(" #n ")" ::: "memory")
; #define PG8_BAR __builtin_amdgcn_s_barrier()
; #define PG8_SCHED __builtin_amdgcn_sched_barrier(0)
; template <class Epi, class Sched, bool ALIGN_EPI = false, bool SP2 = false>
; __device__ __forceinline__ void gemm_phase(PG8_LAS unsigned char* lds, const Gemm g, const Sched& S, const Epi& E) {
;     ...
;             PG8_WAIT_V(8); PG8_WAIT_L(0); PG8_BAR; PG8_MMA(0, 0, At, B0); PG8_MMA(0, 1, At, B1); PG8_BAR; PG8_SCHED;
;             PG8_LDA(At, 0, 1); PG8_STAGE(PG8_SB(0, 0), b2, voffB); PG8_STAGE(PG8_SB(0, 1), b2 + hstep, voffB); PG8_STAGE(PG8_SA(0, 0), a2, voffA);
;             PG8_WAIT_V(8); PG8_WAIT_L(0); PG8_BAR; PG8_MMA(1, 0, At, B0); PG8_MMA(1, 1, At, B1); PG8_BAR; PG8_SCHED;
	v_mfma_f32_16x16x32_bf16 v[156:159], v[76:79], v[174:177], v[156:159]
	v_mfma_f32_16x16x32_bf16 v[128:131], v[84:87], v[174:177], v[128:131]
	v_mfma_f32_16x16x32_bf16 v[152:155], v[76:79], v[182:185], v[152:155]
	v_mfma_f32_16x16x32_bf16 v[148:151], v[84:87], v[182:185], v[148:151]
	v_mfma_f32_16x16x32_bf16 v[124:127], v[76:79], v[198:201], v[124:127]
	v_mfma_f32_16x16x32_bf16 v[120:123], v[84:87], v[198:201], v[120:123]
	v_mfma_f32_16x16x32_bf16 v[112:115], v[76:79], v[220:223], v[112:115]
	v_mfma_f32_16x16x32_bf16 v[64:67], v[84:87], v[220:223], v[64:67]
	v_mfma_f32_16x16x32_bf16 v[156:159], v[80:83], v[178:181], v[156:159]
	v_mfma_f32_16x16x32_bf16 v[128:131], v[88:91], v[178:181], v[128:131]
	v_mfma_f32_16x16x32_bf16 v[152:155], v[80:83], v[194:197], v[152:155]
	v_mfma_f32_16x16x32_bf16 v[148:151], v[88:91], v[194:197], v[148:151]
	v_mfma_f32_16x16x32_bf16 v[124:127], v[80:83], v[202:205], v[124:127]
	v_mfma_f32_16x16x32_bf16 v[120:123], v[88:91], v[202:205], v[120:123]
	v_mfma_f32_16x16x32_bf16 v[112:115], v[80:83], v[224:227], v[112:115]
	v_mfma_f32_16x16x32_bf16 v[64:67], v[88:91], v[224:227], v[64:67]
	s_setprio 0
	s_setprio 1
	v_mfma_f32_16x16x32_bf16 v[144:147], v[92:95], v[174:177], v[144:147]
	v_mfma_f32_16x16x32_bf16 v[140:143], v[108:111], v[174:177], v[140:143]
	v_mfma_f32_16x16x32_bf16 v[136:139], v[92:95], v[182:185], v[136:139]
	v_mfma_f32_16x16x32_bf16 v[132:135], v[108:111], v[182:185], v[132:135]
	v_mfma_f32_16x16x32_bf16 v[104:107], v[92:95], v[198:201], v[104:107]
	v_mfma_f32_16x16x32_bf16 v[96:99], v[108:111], v[198:201], v[96:99]
	v_mfma_f32_16x16x32_bf16 v[72:75], v[92:95], v[220:223], v[72:75]
	v_mfma_f32_16x16x32_bf16 v[68:71], v[108:111], v[220:223], v[68:71]
	v_mfma_f32_16x16x32_bf16 v[144:147], v[100:103], v[178:181], v[144:147]
	v_mfma_f32_16x16x32_bf16 v[140:143], v[116:119], v[178:181], v[140:143]
	v_mfma_f32_16x16x32_bf16 v[136:139], v[100:103], v[194:197], v[136:139]
	v_mfma_f32_16x16x32_bf16 v[132:135], v[116:119], v[194:197], v[132:135]
	v_mfma_f32_16x16x32_bf16 v[104:107], v[100:103], v[202:205], v[104:107]
	v_mfma_f32_16x16x32_bf16 v[96:99], v[116:119], v[202:205], v[96:99]
	v_mfma_f32_16x16x32_bf16 v[72:75], v[100:103], v[224:227], v[72:75]
	v_mfma_f32_16x16x32_bf16 v[68:71], v[116:119], v[224:227], v[68:71]
	s_barrier
	s_setprio 0
	s_add_i32 s72, s72, s52
	v_lshl_add_u64 v[186:187], s[50:51], 0, v[164:165]
	s_mov_b32 m0, s72
	ds_read_b128 v[174:177], v218 offset:16384
	ds_read_b128 v[178:181], v218 offset:17408
	ds_read_b128 v[182:185], v218 offset:18432
	ds_read_b128 v[194:197], v218 offset:19456
	ds_read_b128 v[198:201], v218 offset:20480
	ds_read_b128 v[202:205], v218 offset:21504
	ds_read_b128 v[220:223], v218 offset:22528
	ds_read_b128 v[224:227], v218 offset:23552
	global_load_lds_dwordx4 v[186:187], off
	s_add_i32 m0, s72, 0x2000
	s_add_u32 s72, s50, 0x40000
	v_lshl_add_u64 v[228:229], s[50:51], 0, v[160:161]
	s_addc_u32 s73, s51, 0
	s_add_i32 s74, s74, s52
	global_load_lds_dwordx4 v[228:229], off
	v_lshl_add_u64 v[242:243], s[72:73], 0, v[164:165]
	s_mov_b32 m0, s74
	v_lshl_add_u64 v[244:245], vcc, 0, v[162:163]
	global_load_lds_dwordx4 v[242:243], off
	v_lshl_add_u64 v[242:243], s[72:73], 0, v[160:161]
	s_add_i32 m0, s74, 0x2000
	s_nop 0
	global_load_lds_dwordx4 v[242:243], off
	v_lshl_add_u64 v[242:243], vcc, 0, v[166:167]
	s_mov_b32 m0, s53
	s_nop 0
	global_load_lds_dwordx4 v[242:243], off
	s_mov_b32 m0, s80
	s_nop 0
	global_load_lds_dwordx4 v[244:245], off
	s_waitcnt vmcnt(8)
	s_waitcnt lgkmcnt(0)
	s_setprio 1
	s_barrier

; #define PG8_STAGE(bufoff, gbase, voff) do { _Pragma("unroll") for (int _i = 0; _i < 2; ++_i) \
;         __builtin_amdgcn_global_load_lds((const unsigned*)((const char*)(gbase) + (voff)[_i]), (PG8_LAS unsigned*)(lds + (bufoff) + ldsw + _i * 8192), 16, 0, 0); } while (0)
; #define PG8_LDA(dst, b, h) do { _Pragma("unroll") for (int m = 0; m < 4; ++m) _Pragma("unroll") for (int k = 0; k < 2; ++k) dst[m][k] = *(const PG8_LAS bf16x8*)(lds + PG8_SA(b, h) + aoff + m * 2048 + k * 1024); } while (0)
; #define PG8_LDB(dst, b, h) do { _Pragma("unroll") for (int n = 0; n < 2; ++n) _Pragma("unroll") for (int k = 0; k < 2; ++k) dst[n][k] = *(const PG8_LAS bf16x8*)(lds + PG8_SB(b, h) + boff + n * 2048 + k * 1024); } while (0)
; #define PG8_MMA(ai, bj, At, Bt) do { __builtin_amdgcn_s_setprio(1); _Pragma("unroll") for (int m = 0; m < 4; ++m) _Pragma("unroll") for (int n = 0; n < 2; ++n) _Pragma("unroll") for (int k = 0; k < 2; ++k) \
;         acc[ai][bj][m][n] = __builtin_amdgcn_mfma_f32_16x16x32_bf16(Bt[n][k], At[m][k], acc[ai][bj][m][n], 0, 0, 0); __builtin_amdgcn_s_setprio(0); } while (0)
; #define PG8_WAIT_V(n) asm volatile("s_waitcnt vmcnt(" #n ")" ::: "memory")
; #define PG8_WAIT_L(n) asm volatile("s_waitcnt lgkmcnt(" #n ")" ::: "memory")
; #define PG8_BAR __builtin_amdgcn_s_barrier()
; #define PG8_SCHED __builtin_amdgcn_sched_barrier(0)
; template <class Epi, class Sched, bool ALIGN_EPI = false, bool SP2 = false>
; __device__ __forceinline__ void gemm_phase(PG8_LAS unsigned char* lds, const Gemm g, const Sched& S, const Epi& E) {
;     ...
;             PG8_WAIT_V(8); PG8_WAIT_L(0); PG8_BAR; PG8_MMA(1, 0, At, B0); PG8_MMA(1, 1, At, B1); PG8_BAR; PG8_SCHED;
;             PG8_LDB(B0, 1, 0); PG8_LDB(B1, 1, 1); PG8_SCHED; PG8_LDA(At, 1, 0); PG8_STAGE(PG8_SA(0, 1), a2 + hstep, voffA);
;             PG8_WAIT_V(8); PG8_WAIT_L(0); PG8_BAR; PG8_MMA(0, 0, At, B0); PG8_MMA(0, 1, At, B1); PG8_BAR; PG8_SCHED;
	v_mfma_f32_16x16x32_bf16 v[32:35], v[76:79], v[174:177], v[32:35]
	v_mfma_f32_16x16x32_bf16 v[24:27], v[84:87], v[174:177], v[24:27]
	v_mfma_f32_16x16x32_bf16 v[60:63], v[76:79], v[182:185], v[60:63]
	v_mfma_f32_16x16x32_bf16 v[52:55], v[84:87], v[182:185], v[52:55]
	v_mfma_f32_16x16x32_bf16 v[44:47], v[76:79], v[198:201], v[44:47]
	v_mfma_f32_16x16x32_bf16 v[36:39], v[84:87], v[198:201], v[36:39]
	v_mfma_f32_16x16x32_bf16 v[12:15], v[76:79], v[220:223], v[12:15]
	v_mfma_f32_16x16x32_bf16 v[0:3], v[84:87], v[220:223], v[0:3]
	v_mfma_f32_16x16x32_bf16 v[32:35], v[80:83], v[178:181], v[32:35]
	v_mfma_f32_16x16x32_bf16 v[24:27], v[88:91], v[178:181], v[24:27]
	v_mfma_f32_16x16x32_bf16 v[60:63], v[80:83], v[194:197], v[60:63]
	v_mfma_f32_16x16x32_bf16 v[52:55], v[88:91], v[194:197], v[52:55]
	v_mfma_f32_16x16x32_bf16 v[44:47], v[80:83], v[202:205], v[44:47]
	v_mfma_f32_16x16x32_bf16 v[36:39], v[88:91], v[202:205], v[36:39]
	v_mfma_f32_16x16x32_bf16 v[12:15], v[80:83], v[224:227], v[12:15]
	v_mfma_f32_16x16x32_bf16 v[0:3], v[88:91], v[224:227], v[0:3]
	s_setprio 0
	s_setprio 1
	v_mfma_f32_16x16x32_bf16 v[56:59], v[92:95], v[174:177], v[56:59]
	v_mfma_f32_16x16x32_bf16 v[48:51], v[108:111], v[174:177], v[48:51]
	v_mfma_f32_16x16x32_bf16 v[40:43], v[92:95], v[182:185], v[40:43]
	v_mfma_f32_16x16x32_bf16 v[28:31], v[108:111], v[182:185], v[28:31]
	v_mfma_f32_16x16x32_bf16 v[20:23], v[92:95], v[198:201], v[20:23]
	v_mfma_f32_16x16x32_bf16 v[16:19], v[108:111], v[198:201], v[16:19]
	v_mfma_f32_16x16x32_bf16 v[8:11], v[92:95], v[220:223], v[8:11]
	v_mfma_f32_16x16x32_bf16 v[4:7], v[108:111], v[220:223], v[4:7]
	v_mfma_f32_16x16x32_bf16 v[56:59], v[100:103], v[178:181], v[56:59]
	v_mfma_f32_16x16x32_bf16 v[48:51], v[116:119], v[178:181], v[48:51]
	v_mfma_f32_16x16x32_bf16 v[40:43], v[100:103], v[194:197], v[40:43]
	v_mfma_f32_16x16x32_bf16 v[28:31], v[116:119], v[194:197], v[28:31]
	v_mfma_f32_16x16x32_bf16 v[20:23], v[100:103], v[202:205], v[20:23]
	v_mfma_f32_16x16x32_bf16 v[16:19], v[116:119], v[202:205], v[16:19]
	v_mfma_f32_16x16x32_bf16 v[8:11], v[100:103], v[224:227], v[8:11]
	v_mfma_f32_16x16x32_bf16 v[4:7], v[116:119], v[224:227], v[4:7]
	s_barrier
	s_setprio 0
	s_add_i32 s74, 0, 0x18000
	s_add_i32 s75, 0, 0x1c000
	v_add_u32_e32 v88, s74, v208
	v_add_u32_e32 v116, s75, v208
	ds_read_b128 v[76:79], v88
	ds_read_b128 v[80:83], v88 offset:1024
	ds_read_b128 v[84:87], v88 offset:2048
	ds_read_b128 v[88:91], v88 offset:3072
	ds_read_b128 v[92:95], v116
	ds_read_b128 v[100:103], v116 offset:1024
	ds_read_b128 v[108:111], v116 offset:2048
	ds_read_b128 v[116:119], v116 offset:3072
	s_add_u32 s72, vcc_lo, 0x40000
	s_addc_u32 s73, vcc_hi, 0
	s_mov_b32 m0, s68
	v_lshl_add_u64 v[246:247], s[72:73], 0, v[166:167]
	ds_read_b128 v[174:177], v218 offset:32768
	ds_read_b128 v[178:181], v218 offset:33792
	ds_read_b128 v[182:185], v218 offset:34816
	ds_read_b128 v[194:197], v218 offset:35840
	ds_read_b128 v[198:201], v218 offset:36864
	ds_read_b128 v[202:205], v218 offset:37888
	ds_read_b128 v[220:223], v218 offset:38912
	ds_read_b128 v[224:227], v218 offset:39936
	global_load_lds_dwordx4 v[246:247], off
	v_lshl_add_u64 v[246:247], s[72:73], 0, v[162:163]
	s_mov_b32 m0, s69
	s_nop 0
	global_load_lds_dwordx4 v[246:247], off
	s_waitcnt vmcnt(8)
	s_waitcnt lgkmcnt(0)
	s_setprio 1
	s_barrier

; #define PG8_STAGE(bufoff, gbase, voff) do { _Pragma("unroll") for (int _i = 0; _i < 2; ++_i) \
;         __builtin_amdgcn_global_load_lds((const unsigned*)((const char*)(gbase) + (voff)[_i]), (PG8_LAS unsigned*)(lds + (bufoff) + ldsw + _i * 8192), 16, 0, 0); } while (0)
; #define PG8_LDA(dst, b, h) do { _Pragma("unroll") for (int m = 0; m < 4; ++m) _Pragma("unroll") for (int k = 0; k < 2; ++k) dst[m][k] = *(const PG8_LAS bf16x8*)(lds + PG8_SA(b, h) + aoff + m * 2048 + k * 1024); } while (0)
; #define PG8_MMA(ai, bj, At, Bt) do { __builtin_amdgcn_s_setprio(1); _Pragma("unroll") for (int m = 0; m < 4; ++m) _Pragma("unroll") for (int n = 0; n < 2; ++n) _Pragma("unroll") for (int k = 0; k < 2; ++k) \
;         acc[ai][bj][m][n] = __builtin_amdgcn_mfma_f32_16x16x32_bf16(Bt[n][k], At[m][k], acc[ai][bj][m][n], 0, 0, 0); __builtin_amdgcn_s_setprio(0); } while (0)
; #define PG8_WAIT_V(n) asm volatile("s_waitcnt vmcnt(" #n ")" ::: "memory")
; #define PG8_WAIT_L(n) asm volatile("s_waitcnt lgkmcnt(" #n ")" ::: "memory")
; #define PG8_BAR __builtin_amdgcn_s_barrier()
; #define PG8_SCHED __builtin_amdgcn_sched_barrier(0)
; template <class Epi, class Sched, bool ALIGN_EPI = false, bool SP2 = false>
; __device__ __forceinline__ void gemm_phase(PG8_LAS unsigned char* lds, const Gemm g, const Sched& S, const Epi& E) {
;     ...
;             PG8_WAIT_V(8); PG8_WAIT_L(0); PG8_BAR; PG8_MMA(0, 0, At, B0); PG8_MMA(0, 1, At, B1); PG8_BAR; PG8_SCHED;
;             PG8_LDA(At, 1, 1); PG8_STAGE(PG8_SB(1, 0), b3, voffB); PG8_STAGE(PG8_SB(1, 1), b3 + hstep, voffB); PG8_STAGE(PG8_SA(1, 0), a3, voffA);
;             PG8_WAIT_V(8); PG8_WAIT_L(0); PG8_BAR; PG8_MMA(1, 0, At, B0); PG8_MMA(1, 1, At, B1); PG8_BAR; PG8_SCHED;
	v_mfma_f32_16x16x32_bf16 v[156:159], v[76:79], v[174:177], v[156:159]
	v_mfma_f32_16x16x32_bf16 v[128:131], v[84:87], v[174:177], v[128:131]
	v_mfma_f32_16x16x32_bf16 v[152:155], v[76:79], v[182:185], v[152:155]
	v_mfma_f32_16x16x32_bf16 v[148:151], v[84:87], v[182:185], v[148:151]
	v_mfma_f32_16x16x32_bf16 v[124:127], v[76:79], v[198:201], v[124:127]
	v_mfma_f32_16x16x32_bf16 v[120:123], v[84:87], v[198:201], v[120:123]
	v_mfma_f32_16x16x32_bf16 v[112:115], v[76:79], v[220:223], v[112:115]
	v_mfma_f32_16x16x32_bf16 v[64:67], v[84:87], v[220:223], v[64:67]
	v_mfma_f32_16x16x32_bf16 v[156:159], v[80:83], v[178:181], v[156:159]
	v_mfma_f32_16x16x32_bf16 v[128:131], v[88:91], v[178:181], v[128:131]
	v_mfma_f32_16x16x32_bf16 v[152:155], v[80:83], v[194:197], v[152:155]
	v_mfma_f32_16x16x32_bf16 v[148:151], v[88:91], v[194:197], v[148:151]
	v_mfma_f32_16x16x32_bf16 v[124:127], v[80:83], v[202:205], v[124:127]
	v_mfma_f32_16x16x32_bf16 v[120:123], v[88:91], v[202:205], v[120:123]
	v_mfma_f32_16x16x32_bf16 v[112:115], v[80:83], v[224:227], v[112:115]
	v_mfma_f32_16x16x32_bf16 v[64:67], v[88:91], v[224:227], v[64:67]
	s_setprio 0
	s_setprio 1
	v_mfma_f32_16x16x32_bf16 v[144:147], v[92:95], v[174:177], v[144:147]
	v_mfma_f32_16x16x32_bf16 v[140:143], v[108:111], v[174:177], v[140:143]
	v_mfma_f32_16x16x32_bf16 v[136:139], v[92:95], v[182:185], v[136:139]
	v_mfma_f32_16x16x32_bf16 v[132:135], v[108:111], v[182:185], v[132:135]
	v_mfma_f32_16x16x32_bf16 v[104:107], v[92:95], v[198:201], v[104:107]
	v_mfma_f32_16x16x32_bf16 v[96:99], v[108:111], v[198:201], v[96:99]
	v_mfma_f32_16x16x32_bf16 v[72:75], v[92:95], v[220:223], v[72:75]
	v_mfma_f32_16x16x32_bf16 v[68:71], v[108:111], v[220:223], v[68:71]
	v_mfma_f32_16x16x32_bf16 v[144:147], v[100:103], v[178:181], v[144:147]
	v_mfma_f32_16x16x32_bf16 v[140:143], v[116:119], v[178:181], v[140:143]
	v_mfma_f32_16x16x32_bf16 v[136:139], v[100:103], v[194:197], v[136:139]
	v_mfma_f32_16x16x32_bf16 v[132:135], v[116:119], v[194:197], v[132:135]
	v_mfma_f32_16x16x32_bf16 v[104:107], v[100:103], v[202:205], v[104:107]
	v_mfma_f32_16x16x32_bf16 v[96:99], v[116:119], v[202:205], v[96:99]
	v_mfma_f32_16x16x32_bf16 v[72:75], v[100:103], v[224:227], v[72:75]
	v_mfma_f32_16x16x32_bf16 v[68:71], v[116:119], v[224:227], v[68:71]
	s_barrier
	s_setprio 0
	s_add_i32 s72, s74, s52
	v_lshl_add_u64 v[186:187], v[186:187], 0, s[90:91]
	s_mov_b32 m0, s72
	ds_read_b128 v[174:177], v218 offset:49152
	ds_read_b128 v[178:181], v218 offset:50176
	ds_read_b128 v[182:185], v218 offset:51200
	ds_read_b128 v[194:197], v218 offset:52224
	ds_read_b128 v[198:201], v218 offset:53248
	ds_read_b128 v[202:205], v218 offset:54272
	ds_read_b128 v[220:223], v218 offset:55296
	ds_read_b128 v[224:227], v218 offset:56320
	global_load_lds_dwordx4 v[186:187], off
	s_add_i32 m0, s72, 0x2000
	s_add_u32 s50, s50, 0x40080
	v_lshl_add_u64 v[186:187], v[228:229], 0, s[90:91]
	s_addc_u32 s51, s51, 0
	s_add_i32 s72, s75, s52
	global_load_lds_dwordx4 v[186:187], off
	v_lshl_add_u64 v[186:187], s[50:51], 0, v[164:165]
	s_mov_b32 m0, s72
	s_nop 0
	global_load_lds_dwordx4 v[186:187], off
	v_lshl_add_u64 v[186:187], s[50:51], 0, v[160:161]
	s_add_i32 m0, s72, 0x2000
	s_nop 0
	global_load_lds_dwordx4 v[186:187], off
	v_lshl_add_u64 v[186:187], v[242:243], 0, s[90:91]
	s_mov_b32 m0, s26
	s_nop 0
	global_load_lds_dwordx4 v[186:187], off
	v_lshl_add_u64 v[186:187], v[244:245], 0, s[90:91]
	s_mov_b32 m0, s27
	s_nop 0
	global_load_lds_dwordx4 v[186:187], off
	s_waitcnt vmcnt(8)
	s_waitcnt lgkmcnt(0)
	s_setprio 1
	s_barrier

; #define PG8_STAGE(bufoff, gbase, voff) do { _Pragma("unroll") for (int _i = 0; _i < 2; ++_i) \
;         __builtin_amdgcn_global_load_lds((const unsigned*)((const char*)(gbase) + (voff)[_i]), (PG8_LAS unsigned*)(lds + (bufoff) + ldsw + _i * 8192), 16, 0, 0); } while (0)
; #define PG8_LDA(dst, b, h) do { _Pragma("unroll") for (int m = 0; m < 4; ++m) _Pragma("unroll") for (int k = 0; k < 2; ++k) dst[m][k] = *(const PG8_LAS bf16x8*)(lds + PG8_SA(b, h) + aoff + m * 2048 + k * 1024); } while (0)
; #define PG8_LDB(dst, b, h) do { _Pragma("unroll") for (int n = 0; n < 2; ++n) _Pragma("unroll") for (int k = 0; k < 2; ++k) dst[n][k] = *(const PG8_LAS bf16x8*)(lds + PG8_SB(b, h) + boff + n * 2048 + k * 1024); } while (0)
; template <class Epi, class Sched, bool ALIGN_EPI = false, bool SP2 = false>
; __device__ __forceinline__ void gemm_phase(PG8_LAS unsigned char* lds, const Gemm g, const Sched& S, const Epi& E) {
;     ...
;             PG8_WAIT_V(8); PG8_WAIT_L(0); PG8_BAR; PG8_MMA(1, 0, At, B0); PG8_MMA(1, 1, At, B1); PG8_BAR; PG8_SCHED;
;             } else {
;             PG8_LDB(B0, 0, 0); PG8_SCHED; PG8_LDA(At, 0, 0); PG8_STAGE(PG8_SA(1, 1), a1 + hstep, voffA);
;             PG8_WAIT_L(8); PG8_BAR; PG8_WAIT_L(0); PG8_MMA(0, 0, At, B0); PG8_BAR; PG8_SCHED;
;             PG8_LDB(B1, 0, 1); PG8_STAGE(PG8_SB(0, 0), b2, voffB);
;             PG8_BAR; PG8_WAIT_L(0); PG8_MMA(0, 1, At, B1); PG8_BAR;
;             PG8_LDA(At, 0, 1); PG8_STAGE(PG8_SA(0, 0), a2, voffA);
;             PG8_BAR; PG8_WAIT_L(0); PG8_MMA(1, 0, At, B0); PG8_BAR; PG8_SCHED;
;             PG8_STAGE(PG8_SB(0, 1), b2 + hstep, voffB);
;             PG8_WAIT_V(6); PG8_BAR; PG8_MMA(1, 1, At, B1); PG8_BAR;
;             PG8_LDB(B0, 1, 0); PG8_SCHED; PG8_LDA(At, 1, 0); PG8_STAGE(PG8_SA(0, 1), a2 + hstep, voffA);
;             PG8_WAIT_L(8); PG8_BAR; PG8_WAIT_L(0); PG8_MMA(0, 0, At, B0); PG8_BAR; PG8_SCHED;
;             PG8_LDB(B1, 1, 1); PG8_STAGE(PG8_SB(1, 0), b3, voffB);
;             PG8_BAR; PG8_WAIT_L(0); PG8_MMA(0, 1, At, B1); PG8_BAR;
;             PG8_LDA(At, 1, 1); PG8_STAGE(PG8_SA(1, 0), a3, voffA);
;             PG8_BAR; PG8_WAIT_L(0); PG8_MMA(1, 0, At, B0); PG8_BAR; PG8_SCHED;
;             PG8_STAGE(PG8_SB(1, 1), b3 + hstep, voffB);
;             PG8_WAIT_V(6); PG8_BAR; PG8_MMA(1, 1, At, B1); PG8_BAR;
;             }
;         }
;         if constexpr (ALIGN_EPI) { if (wr == 0) PG8_BAR; }
	v_mfma_f32_16x16x32_bf16 v[32:35], v[76:79], v[174:177], v[32:35]
	v_mfma_f32_16x16x32_bf16 v[24:27], v[84:87], v[174:177], v[24:27]
	v_mfma_f32_16x16x32_bf16 v[60:63], v[76:79], v[182:185], v[60:63]
	v_mfma_f32_16x16x32_bf16 v[52:55], v[84:87], v[182:185], v[52:55]
	v_mfma_f32_16x16x32_bf16 v[44:47], v[76:79], v[198:201], v[44:47]
	v_mfma_f32_16x16x32_bf16 v[36:39], v[84:87], v[198:201], v[36:39]
	v_mfma_f32_16x16x32_bf16 v[12:15], v[76:79], v[220:223], v[12:15]
	v_mfma_f32_16x16x32_bf16 v[0:3], v[84:87], v[220:223], v[0:3]
	v_mfma_f32_16x16x32_bf16 v[32:35], v[80:83], v[178:181], v[32:35]
	v_mfma_f32_16x16x32_bf16 v[24:27], v[88:91], v[178:181], v[24:27]
	v_mfma_f32_16x16x32_bf16 v[60:63], v[80:83], v[194:197], v[60:63]
	v_mfma_f32_16x16x32_bf16 v[52:55], v[88:91], v[194:197], v[52:55]
	v_mfma_f32_16x16x32_bf16 v[44:47], v[80:83], v[202:205], v[44:47]
	v_mfma_f32_16x16x32_bf16 v[36:39], v[88:91], v[202:205], v[36:39]
	v_mfma_f32_16x16x32_bf16 v[12:15], v[80:83], v[224:227], v[12:15]
	v_mfma_f32_16x16x32_bf16 v[0:3], v[88:91], v[224:227], v[0:3]
	s_setprio 0
	s_setprio 1
	v_mfma_f32_16x16x32_bf16 v[56:59], v[92:95], v[174:177], v[56:59]
	v_mfma_f32_16x16x32_bf16 v[48:51], v[108:111], v[174:177], v[48:51]
	v_mfma_f32_16x16x32_bf16 v[40:43], v[92:95], v[182:185], v[40:43]
	v_mfma_f32_16x16x32_bf16 v[28:31], v[108:111], v[182:185], v[28:31]
	v_mfma_f32_16x16x32_bf16 v[20:23], v[92:95], v[198:201], v[20:23]
	v_mfma_f32_16x16x32_bf16 v[16:19], v[108:111], v[198:201], v[16:19]
	v_mfma_f32_16x16x32_bf16 v[8:11], v[92:95], v[220:223], v[8:11]
	v_mfma_f32_16x16x32_bf16 v[4:7], v[108:111], v[220:223], v[4:7]
	v_mfma_f32_16x16x32_bf16 v[56:59], v[100:103], v[178:181], v[56:59]
	v_mfma_f32_16x16x32_bf16 v[48:51], v[116:119], v[178:181], v[48:51]
	v_mfma_f32_16x16x32_bf16 v[40:43], v[100:103], v[194:197], v[40:43]
	v_mfma_f32_16x16x32_bf16 v[28:31], v[116:119], v[194:197], v[28:31]
	v_mfma_f32_16x16x32_bf16 v[20:23], v[100:103], v[202:205], v[20:23]
	v_mfma_f32_16x16x32_bf16 v[16:19], v[116:119], v[202:205], v[16:19]
	v_mfma_f32_16x16x32_bf16 v[8:11], v[100:103], v[224:227], v[8:11]
	v_mfma_f32_16x16x32_bf16 v[4:7], v[116:119], v[224:227], v[4:7]
	s_barrier
	s_setprio 0
	s_add_i32 s71, s71, 2
	s_add_u32 s44, s44, 0x100
	s_addc_u32 s45, s45, 0
	s_add_u32 s39, s39, 0x100
	s_addc_u32 s57, s57, 0
	s_cmp_gt_u32 s71, 13
	s_cbranch_scc0 .LBB0_180
	s_and_b64 vcc, exec, s[28:29]
	s_cbranch_vccz .LBB0_183
	s_barrier

; #define PG8_STAGE(bufoff, gbase, voff) do { _Pragma("unroll") for (int _i = 0; _i < 2; ++_i) \
;         __builtin_amdgcn_global_load_lds((const unsigned*)((const char*)(gbase) + (voff)[_i]), (PG8_LAS unsigned*)(lds + (bufoff) + ldsw + _i * 8192), 16, 0, 0); } while (0)
; #define PG8_LDA(dst, b, h) do { _Pragma("unroll") for (int m = 0; m < 4; ++m) _Pragma("unroll") for (int k = 0; k < 2; ++k) dst[m][k] = *(const PG8_LAS bf16x8*)(lds + PG8_SA(b, h) + aoff + m * 2048 + k * 1024); } while (0)
; #define PG8_LDB(dst, b, h) do { _Pragma("unroll") for (int n = 0; n < 2; ++n) _Pragma("unroll") for (int k = 0; k < 2; ++k) dst[n][k] = *(const PG8_LAS bf16x8*)(lds + PG8_SB(b, h) + boff + n * 2048 + k * 1024); } while (0)
; #define PG8_MMA(ai, bj, At, Bt) do { __builtin_amdgcn_s_setprio(1); _Pragma("unroll") for (int m = 0; m < 4; ++m) _Pragma("unroll") for (int n = 0; n < 2; ++n) _Pragma("unroll") for (int k = 0; k < 2; ++k) \
;         acc[ai][bj][m][n] = __builtin_amdgcn_mfma_f32_16x16x32_bf16(Bt[n][k], At[m][k], acc[ai][bj][m][n], 0, 0, 0); __builtin_amdgcn_s_setprio(0); } while (0)
; #define PG8_WAIT_V(n) asm volatile("s_waitcnt vmcnt(" #n ")" ::: "memory")
; #define PG8_WAIT_L(n) asm volatile("s_waitcnt lgkmcnt(" #n ")" ::: "memory")
; #define PG8_BAR __builtin_amdgcn_s_barrier()
; template <class Epi, class Sched, bool ALIGN_EPI = false, bool SP2 = false>
; __device__ __forceinline__ void gemm_phase(PG8_LAS unsigned char* lds, const Gemm g, const Sched& S, const Epi& E) {
;     ...
;         const bool has_next = S.next(ui + 1, nxt);
;         const char* nA = has_next ? (const char*)g.A + (size_t)nxt.pm * tstep : cA; const char* nB = has_next ? (const char*)g.Bt + (size_t)nxt.pn * tstep : cB;
;         for (int t = 0; t < nt; t += 2) {
;             const bool last = (t == nt - 2);
;             const char* a1 = cA + (size_t)(t + 1) * kstep;
;             const char* a2 = last ? nA : cA + (size_t)(t + 2) * kstep; const char* b2 = last ? nB : cB + (size_t)(t + 2) * kstep;
;             const char* a3 = a2 + kstep; const char* b3 = b2 + kstep;
;             if (last && has_next) S.a_ready(nxt);
;             if constexpr (SP2) {
;             PG8_LDB(B0, 0, 0); PG8_LDB(B1, 0, 1); PG8_SCHED; PG8_LDA(At, 0, 0); PG8_STAGE(PG8_SA(1, 1), a1 + hstep, voffA);
;             PG8_WAIT_V(8); PG8_WAIT_L(0); PG8_BAR; PG8_MMA(0, 0, At, B0); PG8_MMA(0, 1, At, B1); PG8_BAR; PG8_SCHED;
.LBB0_577:
	s_add_u32 s38, s36, 0xfffc0080
	s_addc_u32 s39, s37, -1
	s_add_i32 s69, 0, 0x10000
	s_cmp_eq_u32 s49, 12
	s_cselect_b32 s41, s0, s39
	s_cselect_b32 s40, s1, s38
	s_cselect_b32 s39, s4, s29
	s_cselect_b32 s38, s5, s27
	s_add_i32 s72, 0, 0x14000
	v_add_u32_e32 v48, s69, v180
	v_add_u32_e32 v68, s72, v180
	ds_read_b128 v[36:39], v48
	ds_read_b128 v[40:43], v48 offset:1024
	ds_read_b128 v[44:47], v48 offset:2048
	ds_read_b128 v[48:51], v48 offset:3072
	ds_read_b128 v[56:59], v68
	ds_read_b128 v[60:63], v68 offset:1024
	ds_read_b128 v[64:67], v68 offset:2048
	ds_read_b128 v[68:71], v68 offset:3072
	v_lshl_add_u64 v[238:239], s[36:37], 0, v[166:167]
	s_add_i32 m0, s53, 0xc000
	ds_read_b128 v[170:173], v205
	ds_read_b128 v[174:177], v205 offset:1024
	ds_read_b128 v[206:209], v205 offset:2048
	ds_read_b128 v[210:213], v205 offset:3072
	ds_read_b128 v[214:217], v205 offset:4096
	ds_read_b128 v[218:221], v205 offset:5120
	ds_read_b128 v[222:225], v205 offset:6144
	ds_read_b128 v[226:229], v205 offset:7168
	global_load_lds_dwordx4 v[238:239], off
	v_lshl_add_u64 v[238:239], s[36:37], 0, v[168:169]
	s_add_i32 m0, s53, 0xe000
	s_nop 0
	global_load_lds_dwordx4 v[238:239], off
	s_waitcnt vmcnt(8)
	s_waitcnt lgkmcnt(0)
	s_setprio 1
	s_barrier

; #define PG8_STAGE(bufoff, gbase, voff) do { _Pragma("unroll") for (int _i = 0; _i < 2; ++_i) \
;         __builtin_amdgcn_global_load_lds((const unsigned*)((const char*)(gbase) + (voff)[_i]), (PG8_LAS unsigned*)(lds + (bufoff) + ldsw + _i * 8192), 16, 0, 0); } while (0)
; #define PG8_LDA(dst, b, h) do { _Pragma("unroll") for (int m = 0; m < 4; ++m) _Pragma("unroll") for (int k = 0; k < 2; ++k) dst[m][k] = *(const PG8_LAS bf16x8*)(lds + PG8_SA(b, h) + aoff + m * 2048 + k * 1024); } while (0)
; #define PG8_MMA(ai, bj, At, Bt) do { __builtin_amdgcn_s_setprio(1); _Pragma("unroll") for (int m = 0; m < 4; ++m) _Pragma("unroll") for (int n = 0; n < 2; ++n) _Pragma("unroll") for (int k = 0; k < 2; ++k) \
;         acc[ai][bj][m][n] = __builtin_amdgcn_mfma_f32_16x16x32_bf16(Bt[n][k], At[m][k], acc[ai][bj][m][n], 0, 0, 0); __builtin_amdgcn_s_setprio(0); } while (0)
; #define PG8_WAIT_V(n) asm volatile("s_waitcnt vmcnt(" #n ")" ::: "memory")
; #define PG8_WAIT_L(n) asm volatile("s_waitcnt lgkmcnt(" #n ")" ::: "memory")
; #define PG8_BAR __builtin_amdgcn_s_barrier()
; #define PG8_SCHED __builtin_amdgcn_sched_barrier(0)
; template <class Epi, class Sched, bool ALIGN_EPI = false, bool SP2 = false>
; __device__ __forceinline__ void gemm_phase(PG8_LAS unsigned char* lds, const Gemm g, const Sched& S, const Epi& E) {
;     ...
;             PG8_WAIT_V(8); PG8_WAIT_L(0); PG8_BAR; PG8_MMA(0, 0, At, B0); PG8_MMA(0, 1, At, B1); PG8_BAR; PG8_SCHED;
;             PG8_LDA(At, 0, 1); PG8_STAGE(PG8_SB(0, 0), b2, voffB); PG8_STAGE(PG8_SB(0, 1), b2 + hstep, voffB); PG8_STAGE(PG8_SA(0, 0), a2, voffA);
;             PG8_WAIT_V(8); PG8_WAIT_L(0); PG8_BAR; PG8_MMA(1, 0, At, B0); PG8_MMA(1, 1, At, B1); PG8_BAR; PG8_SCHED;
	v_mfma_f32_16x16x32_bf16 v[156:159], v[36:39], v[170:173], v[156:159]
	v_mfma_f32_16x16x32_bf16 v[152:155], v[44:47], v[170:173], v[152:155]
	v_mfma_f32_16x16x32_bf16 v[140:143], v[36:39], v[206:209], v[140:143]
	v_mfma_f32_16x16x32_bf16 v[136:139], v[44:47], v[206:209], v[136:139]
	v_mfma_f32_16x16x32_bf16 v[124:127], v[36:39], v[214:217], v[124:127]
	v_mfma_f32_16x16x32_bf16 v[120:123], v[44:47], v[214:217], v[120:123]
	v_mfma_f32_16x16x32_bf16 v[108:111], v[36:39], v[222:225], v[108:111]
	v_mfma_f32_16x16x32_bf16 v[104:107], v[44:47], v[222:225], v[104:107]
	v_mfma_f32_16x16x32_bf16 v[156:159], v[40:43], v[174:177], v[156:159]
	v_mfma_f32_16x16x32_bf16 v[152:155], v[48:51], v[174:177], v[152:155]
	v_mfma_f32_16x16x32_bf16 v[140:143], v[40:43], v[210:213], v[140:143]
	v_mfma_f32_16x16x32_bf16 v[136:139], v[48:51], v[210:213], v[136:139]
	v_mfma_f32_16x16x32_bf16 v[124:127], v[40:43], v[218:221], v[124:127]
	v_mfma_f32_16x16x32_bf16 v[120:123], v[48:51], v[218:221], v[120:123]
	v_mfma_f32_16x16x32_bf16 v[108:111], v[40:43], v[226:229], v[108:111]
	v_mfma_f32_16x16x32_bf16 v[104:107], v[48:51], v[226:229], v[104:107]
	s_setprio 0
	s_setprio 1
	v_mfma_f32_16x16x32_bf16 v[148:151], v[56:59], v[170:173], v[148:151]
	v_mfma_f32_16x16x32_bf16 v[144:147], v[64:67], v[170:173], v[144:147]
	v_mfma_f32_16x16x32_bf16 v[132:135], v[56:59], v[206:209], v[132:135]
	v_mfma_f32_16x16x32_bf16 v[128:131], v[64:67], v[206:209], v[128:131]
	v_mfma_f32_16x16x32_bf16 v[116:119], v[56:59], v[214:217], v[116:119]
	v_mfma_f32_16x16x32_bf16 v[112:115], v[64:67], v[214:217], v[112:115]
	v_mfma_f32_16x16x32_bf16 v[100:103], v[56:59], v[222:225], v[100:103]
	v_mfma_f32_16x16x32_bf16 v[96:99], v[64:67], v[222:225], v[96:99]
	v_mfma_f32_16x16x32_bf16 v[148:151], v[60:63], v[174:177], v[148:151]
	v_mfma_f32_16x16x32_bf16 v[144:147], v[68:71], v[174:177], v[144:147]
	v_mfma_f32_16x16x32_bf16 v[132:135], v[60:63], v[210:213], v[132:135]
	v_mfma_f32_16x16x32_bf16 v[128:131], v[68:71], v[210:213], v[128:131]
	v_mfma_f32_16x16x32_bf16 v[116:119], v[60:63], v[218:221], v[116:119]
	v_mfma_f32_16x16x32_bf16 v[112:115], v[68:71], v[218:221], v[112:115]
	v_mfma_f32_16x16x32_bf16 v[100:103], v[60:63], v[226:229], v[100:103]
	v_mfma_f32_16x16x32_bf16 v[96:99], v[68:71], v[226:229], v[96:99]
	s_barrier
	s_setprio 0
	s_add_i32 s69, s69, s6
	v_lshl_add_u64 v[238:239], s[38:39], 0, v[188:189]
	s_mov_b32 m0, s69
	ds_read_b128 v[170:173], v205 offset:16384
	ds_read_b128 v[174:177], v205 offset:17408
	ds_read_b128 v[206:209], v205 offset:18432
	ds_read_b128 v[210:213], v205 offset:19456
	ds_read_b128 v[214:217], v205 offset:20480
	ds_read_b128 v[218:221], v205 offset:21504
	ds_read_b128 v[222:225], v205 offset:22528
	ds_read_b128 v[226:229], v205 offset:23552
	global_load_lds_dwordx4 v[238:239], off
	s_add_i32 m0, s69, 0x2000
	s_add_u32 s70, s38, 0x40000
	v_lshl_add_u64 v[240:241], s[38:39], 0, v[160:161]
	s_addc_u32 s71, s39, 0
	s_add_i32 s69, s72, s6
	global_load_lds_dwordx4 v[240:241], off
	v_lshl_add_u64 v[242:243], s[70:71], 0, v[188:189]
	s_mov_b32 m0, s69
	v_lshl_add_u64 v[246:247], s[40:41], 0, v[164:165]
	global_load_lds_dwordx4 v[242:243], off
	v_lshl_add_u64 v[242:243], s[70:71], 0, v[160:161]
	s_add_i32 m0, s69, 0x2000
	v_lshl_add_u64 v[248:249], s[40:41], 0, v[162:163]
	global_load_lds_dwordx4 v[242:243], off
	s_mov_b32 m0, s53
	s_nop 0
	global_load_lds_dwordx4 v[246:247], off
	s_mov_b32 m0, s54
	s_nop 0
	global_load_lds_dwordx4 v[248:249], off
	s_waitcnt vmcnt(8)
	s_waitcnt lgkmcnt(0)
	s_setprio 1
	s_barrier

; #define PG8_STAGE(bufoff, gbase, voff) do { _Pragma("unroll") for (int _i = 0; _i < 2; ++_i) \
;         __builtin_amdgcn_global_load_lds((const unsigned*)((const char*)(gbase) + (voff)[_i]), (PG8_LAS unsigned*)(lds + (bufoff) + ldsw + _i * 8192), 16, 0, 0); } while (0)
; #define PG8_LDA(dst, b, h) do { _Pragma("unroll") for (int m = 0; m < 4; ++m) _Pragma("unroll") for (int k = 0; k < 2; ++k) dst[m][k] = *(const PG8_LAS bf16x8*)(lds + PG8_SA(b, h) + aoff + m * 2048 + k * 1024); } while (0)
; #define PG8_LDB(dst, b, h) do { _Pragma("unroll") for (int n = 0; n < 2; ++n) _Pragma("unroll") for (int k = 0; k < 2; ++k) dst[n][k] = *(const PG8_LAS bf16x8*)(lds + PG8_SB(b, h) + boff + n * 2048 + k * 1024); } while (0)
; #define PG8_MMA(ai, bj, At, Bt) do { __builtin_amdgcn_s_setprio(1); _Pragma("unroll") for (int m = 0; m < 4; ++m) _Pragma("unroll") for (int n = 0; n < 2; ++n) _Pragma("unroll") for (int k = 0; k < 2; ++k) \
;         acc[ai][bj][m][n] = __builtin_amdgcn_mfma_f32_16x16x32_bf16(Bt[n][k], At[m][k], acc[ai][bj][m][n], 0, 0, 0); __builtin_amdgcn_s_setprio(0); } while (0)
; #define PG8_WAIT_V(n) asm volatile("s_waitcnt vmcnt(" #n ")" ::: "memory")
; #define PG8_WAIT_L(n) asm volatile("s_waitcnt lgkmcnt(" #n ")" ::: "memory")
; #define PG8_BAR __builtin_amdgcn_s_barrier()
; #define PG8_SCHED __builtin_amdgcn_sched_barrier(0)
; template <class Epi, class Sched, bool ALIGN_EPI = false, bool SP2 = false>
; __device__ __forceinline__ void gemm_phase(PG8_LAS unsigned char* lds, const Gemm g, const Sched& S, const Epi& E) {
;     ...
;             PG8_WAIT_V(8); PG8_WAIT_L(0); PG8_BAR; PG8_MMA(1, 0, At, B0); PG8_MMA(1, 1, At, B1); PG8_BAR; PG8_SCHED;
;             PG8_LDB(B0, 1, 0); PG8_LDB(B1, 1, 1); PG8_SCHED; PG8_LDA(At, 1, 0); PG8_STAGE(PG8_SA(0, 1), a2 + hstep, voffA);
;             PG8_WAIT_V(8); PG8_WAIT_L(0); PG8_BAR; PG8_MMA(0, 0, At, B0); PG8_MMA(0, 1, At, B1); PG8_BAR; PG8_SCHED;
	v_mfma_f32_16x16x32_bf16 v[92:95], v[36:39], v[170:173], v[92:95]
	v_mfma_f32_16x16x32_bf16 v[88:91], v[44:47], v[170:173], v[88:91]
	v_mfma_f32_16x16x32_bf16 v[76:79], v[36:39], v[206:209], v[76:79]
	v_mfma_f32_16x16x32_bf16 v[72:75], v[44:47], v[206:209], v[72:75]
	v_mfma_f32_16x16x32_bf16 v[28:31], v[36:39], v[214:217], v[28:31]
	v_mfma_f32_16x16x32_bf16 v[24:27], v[44:47], v[214:217], v[24:27]
	v_mfma_f32_16x16x32_bf16 v[12:15], v[36:39], v[222:225], v[12:15]
	v_mfma_f32_16x16x32_bf16 v[8:11], v[44:47], v[222:225], v[8:11]
	v_mfma_f32_16x16x32_bf16 v[92:95], v[40:43], v[174:177], v[92:95]
	v_mfma_f32_16x16x32_bf16 v[88:91], v[48:51], v[174:177], v[88:91]
	v_mfma_f32_16x16x32_bf16 v[76:79], v[40:43], v[210:213], v[76:79]
	v_mfma_f32_16x16x32_bf16 v[72:75], v[48:51], v[210:213], v[72:75]
	v_mfma_f32_16x16x32_bf16 v[28:31], v[40:43], v[218:221], v[28:31]
	v_mfma_f32_16x16x32_bf16 v[24:27], v[48:51], v[218:221], v[24:27]
	v_mfma_f32_16x16x32_bf16 v[12:15], v[40:43], v[226:229], v[12:15]
	v_mfma_f32_16x16x32_bf16 v[8:11], v[48:51], v[226:229], v[8:11]
	s_setprio 0
	s_setprio 1
	v_mfma_f32_16x16x32_bf16 v[32:35], v[64:67], v[206:209], v[32:35]
	v_mfma_f32_16x16x32_bf16 v[20:23], v[56:59], v[214:217], v[20:23]
	v_mfma_f32_16x16x32_bf16 v[16:19], v[64:67], v[214:217], v[16:19]
	v_mfma_f32_16x16x32_bf16 v[4:7], v[56:59], v[222:225], v[4:7]
	v_mfma_f32_16x16x32_bf16 v[0:3], v[64:67], v[222:225], v[0:3]
	v_mfma_f32_16x16x32_bf16 v[36:39], v[56:59], v[170:173], v[84:87]
	v_mfma_f32_16x16x32_bf16 v[40:43], v[64:67], v[170:173], v[80:83]
	v_mfma_f32_16x16x32_bf16 v[44:47], v[56:59], v[206:209], v[52:55]
	v_mfma_f32_16x16x32_bf16 v[32:35], v[68:71], v[210:213], v[32:35]
	v_mfma_f32_16x16x32_bf16 v[20:23], v[60:63], v[218:221], v[20:23]
	v_mfma_f32_16x16x32_bf16 v[16:19], v[68:71], v[218:221], v[16:19]
	v_mfma_f32_16x16x32_bf16 v[4:7], v[60:63], v[226:229], v[4:7]
	v_mfma_f32_16x16x32_bf16 v[0:3], v[68:71], v[226:229], v[0:3]
	v_mfma_f32_16x16x32_bf16 v[36:39], v[60:63], v[174:177], v[36:39]
	v_mfma_f32_16x16x32_bf16 v[40:43], v[68:71], v[174:177], v[40:43]
	v_mfma_f32_16x16x32_bf16 v[44:47], v[60:63], v[210:213], v[44:47]
	s_barrier
	s_setprio 0
	s_add_i32 s69, 0, 0x18000
	s_add_i32 s70, 0, 0x1c000
	v_add_u32_e32 v60, s69, v180
	v_add_u32_e32 v80, s70, v180
	ds_read_b128 v[48:51], v60
	ds_read_b128 v[52:55], v60 offset:1024
	ds_read_b128 v[56:59], v60 offset:2048
	ds_read_b128 v[60:63], v60 offset:3072
	ds_read_b128 v[64:67], v80
	ds_read_b128 v[68:71], v80 offset:1024
	ds_read_b128 v[170:173], v80 offset:2048
	ds_read_b128 v[174:177], v80 offset:3072
	s_add_u32 s40, s40, 0x40000
	s_addc_u32 s41, s41, 0
	s_mov_b32 m0, s55
	v_lshl_add_u64 v[242:243], s[40:41], 0, v[164:165]
	ds_read_b128 v[80:83], v205 offset:32768
	ds_read_b128 v[84:87], v205 offset:33792
	ds_read_b128 v[206:209], v205 offset:34816
	ds_read_b128 v[210:213], v205 offset:35840
	ds_read_b128 v[214:217], v205 offset:36864
	ds_read_b128 v[218:221], v205 offset:37888
	ds_read_b128 v[222:225], v205 offset:38912
	ds_read_b128 v[226:229], v205 offset:39936
	global_load_lds_dwordx4 v[242:243], off
	v_lshl_add_u64 v[242:243], s[40:41], 0, v[162:163]
	s_mov_b32 m0, s56
	s_nop 0
	global_load_lds_dwordx4 v[242:243], off
	s_waitcnt vmcnt(8)
	s_waitcnt lgkmcnt(0)
	s_setprio 1
	s_barrier

; #define PG8_STAGE(bufoff, gbase, voff) do { _Pragma("unroll") for (int _i = 0; _i < 2; ++_i) \
;         __builtin_amdgcn_global_load_lds((const unsigned*)((const char*)(gbase) + (voff)[_i]), (PG8_LAS unsigned*)(lds + (bufoff) + ldsw + _i * 8192), 16, 0, 0); } while (0)
; #define PG8_LDA(dst, b, h) do { _Pragma("unroll") for (int m = 0; m < 4; ++m) _Pragma("unroll") for (int k = 0; k < 2; ++k) dst[m][k] = *(const PG8_LAS bf16x8*)(lds + PG8_SA(b, h) + aoff + m * 2048 + k * 1024); } while (0)
; #define PG8_MMA(ai, bj, At, Bt) do { __builtin_amdgcn_s_setprio(1); _Pragma("unroll") for (int m = 0; m < 4; ++m) _Pragma("unroll") for (int n = 0; n < 2; ++n) _Pragma("unroll") for (int k = 0; k < 2; ++k) \
;         acc[ai][bj][m][n] = __builtin_amdgcn_mfma_f32_16x16x32_bf16(Bt[n][k], At[m][k], acc[ai][bj][m][n], 0, 0, 0); __builtin_amdgcn_s_setprio(0); } while (0)
; #define PG8_WAIT_V(n) asm volatile("s_waitcnt vmcnt(" #n ")" ::: "memory")
; #define PG8_WAIT_L(n) asm volatile("s_waitcnt lgkmcnt(" #n ")" ::: "memory")
; #define PG8_BAR __builtin_amdgcn_s_barrier()
; #define PG8_SCHED __builtin_amdgcn_sched_barrier(0)
; template <class Epi, class Sched, bool ALIGN_EPI = false, bool SP2 = false>
; __device__ __forceinline__ void gemm_phase(PG8_LAS unsigned char* lds, const Gemm g, const Sched& S, const Epi& E) {
;     ...
;             PG8_WAIT_V(8); PG8_WAIT_L(0); PG8_BAR; PG8_MMA(0, 0, At, B0); PG8_MMA(0, 1, At, B1); PG8_BAR; PG8_SCHED;
;             PG8_LDA(At, 1, 1); PG8_STAGE(PG8_SB(1, 0), b3, voffB); PG8_STAGE(PG8_SB(1, 1), b3 + hstep, voffB); PG8_STAGE(PG8_SA(1, 0), a3, voffA);
;             PG8_WAIT_V(8); PG8_WAIT_L(0); PG8_BAR; PG8_MMA(1, 0, At, B0); PG8_MMA(1, 1, At, B1); PG8_BAR; PG8_SCHED;
	v_mfma_f32_16x16x32_bf16 v[156:159], v[48:51], v[80:83], v[156:159]
	v_mfma_f32_16x16x32_bf16 v[152:155], v[56:59], v[80:83], v[152:155]
	v_mfma_f32_16x16x32_bf16 v[140:143], v[48:51], v[206:209], v[140:143]
	v_mfma_f32_16x16x32_bf16 v[136:139], v[56:59], v[206:209], v[136:139]
	v_mfma_f32_16x16x32_bf16 v[124:127], v[48:51], v[214:217], v[124:127]
	v_mfma_f32_16x16x32_bf16 v[120:123], v[56:59], v[214:217], v[120:123]
	v_mfma_f32_16x16x32_bf16 v[108:111], v[48:51], v[222:225], v[108:111]
	v_mfma_f32_16x16x32_bf16 v[104:107], v[56:59], v[222:225], v[104:107]
	v_mfma_f32_16x16x32_bf16 v[156:159], v[52:55], v[84:87], v[156:159]
	v_mfma_f32_16x16x32_bf16 v[152:155], v[60:63], v[84:87], v[152:155]
	v_mfma_f32_16x16x32_bf16 v[140:143], v[52:55], v[210:213], v[140:143]
	v_mfma_f32_16x16x32_bf16 v[136:139], v[60:63], v[210:213], v[136:139]
	v_mfma_f32_16x16x32_bf16 v[124:127], v[52:55], v[218:221], v[124:127]
	v_mfma_f32_16x16x32_bf16 v[120:123], v[60:63], v[218:221], v[120:123]
	v_mfma_f32_16x16x32_bf16 v[108:111], v[52:55], v[226:229], v[108:111]
	v_mfma_f32_16x16x32_bf16 v[104:107], v[60:63], v[226:229], v[104:107]
	s_setprio 0
	s_setprio 1
	v_mfma_f32_16x16x32_bf16 v[148:151], v[64:67], v[80:83], v[148:151]
	v_mfma_f32_16x16x32_bf16 v[80:83], v[170:173], v[80:83], v[144:147]
	v_mfma_f32_16x16x32_bf16 v[144:147], v[174:177], v[84:87], v[80:83]
	v_mfma_f32_16x16x32_bf16 v[80:83], v[64:67], v[206:209], v[132:135]
	v_mfma_f32_16x16x32_bf16 v[132:135], v[68:71], v[210:213], v[80:83]
	v_mfma_f32_16x16x32_bf16 v[80:83], v[170:173], v[206:209], v[128:131]
	v_mfma_f32_16x16x32_bf16 v[128:131], v[174:177], v[210:213], v[80:83]
	v_mfma_f32_16x16x32_bf16 v[80:83], v[64:67], v[214:217], v[116:119]
	v_mfma_f32_16x16x32_bf16 v[116:119], v[68:71], v[218:221], v[80:83]
	v_mfma_f32_16x16x32_bf16 v[80:83], v[170:173], v[214:217], v[112:115]
	v_mfma_f32_16x16x32_bf16 v[112:115], v[174:177], v[218:221], v[80:83]
	v_mfma_f32_16x16x32_bf16 v[80:83], v[64:67], v[222:225], v[100:103]
	v_mfma_f32_16x16x32_bf16 v[100:103], v[68:71], v[226:229], v[80:83]
	v_mfma_f32_16x16x32_bf16 v[80:83], v[170:173], v[222:225], v[96:99]
	v_mfma_f32_16x16x32_bf16 v[148:151], v[68:71], v[84:87], v[148:151]
	v_mfma_f32_16x16x32_bf16 v[96:99], v[174:177], v[226:229], v[80:83]
	s_barrier
	s_setprio 0
	s_add_i32 s40, s69, s6
	v_lshl_add_u64 v[84:85], v[238:239], 0, s[90:91]
	s_mov_b32 m0, s40
	s_nop 0
	ds_read_b128 v[80:83], v205 offset:49152
	ds_read_b128 v[206:209], v205 offset:50176
	ds_read_b128 v[210:213], v205 offset:51200
	ds_read_b128 v[214:217], v205 offset:52224
	ds_read_b128 v[218:221], v205 offset:53248
	ds_read_b128 v[222:225], v205 offset:54272
	ds_read_b128 v[226:229], v205 offset:55296
	ds_read_b128 v[242:245], v205 offset:56320
	global_load_lds_dwordx4 v[84:85], off
	s_add_i32 m0, s40, 0x2000
	s_add_u32 s38, s38, 0x40080
	v_lshl_add_u64 v[84:85], v[240:241], 0, s[90:91]
	s_addc_u32 s39, s39, 0
	s_add_i32 s40, s70, s6
	global_load_lds_dwordx4 v[84:85], off
	v_lshl_add_u64 v[84:85], s[38:39], 0, v[188:189]
	s_mov_b32 m0, s40
	s_nop 0
	global_load_lds_dwordx4 v[84:85], off
	v_lshl_add_u64 v[84:85], s[38:39], 0, v[160:161]
	s_add_i32 m0, s40, 0x2000
	s_nop 0
	global_load_lds_dwordx4 v[84:85], off
	v_lshl_add_u64 v[84:85], v[246:247], 0, s[90:91]
	s_mov_b32 m0, s57
	s_nop 0
	global_load_lds_dwordx4 v[84:85], off
	v_lshl_add_u64 v[84:85], v[248:249], 0, s[90:91]
	s_mov_b32 m0, s60
	s_nop 0
	global_load_lds_dwordx4 v[84:85], off
	s_waitcnt vmcnt(8)
	s_waitcnt lgkmcnt(0)
	s_setprio 1
	s_barrier

; #define PG8_STAGE(bufoff, gbase, voff) do { _Pragma("unroll") for (int _i = 0; _i < 2; ++_i) \
;         __builtin_amdgcn_global_load_lds((const unsigned*)((const char*)(gbase) + (voff)[_i]), (PG8_LAS unsigned*)(lds + (bufoff) + ldsw + _i * 8192), 16, 0, 0); } while (0)
; #define PG8_LDA(dst, b, h) do { _Pragma("unroll") for (int m = 0; m < 4; ++m) _Pragma("unroll") for (int k = 0; k < 2; ++k) dst[m][k] = *(const PG8_LAS bf16x8*)(lds + PG8_SA(b, h) + aoff + m * 2048 + k * 1024); } while (0)
; #define PG8_LDB(dst, b, h) do { _Pragma("unroll") for (int n = 0; n < 2; ++n) _Pragma("unroll") for (int k = 0; k < 2; ++k) dst[n][k] = *(const PG8_LAS bf16x8*)(lds + PG8_SB(b, h) + boff + n * 2048 + k * 1024); } while (0)
; template <class Epi, class Sched, bool ALIGN_EPI = false, bool SP2 = false>
; __device__ __forceinline__ void gemm_phase(PG8_LAS unsigned char* lds, const Gemm g, const Sched& S, const Epi& E) {
;     ...
;             PG8_WAIT_V(8); PG8_WAIT_L(0); PG8_BAR; PG8_MMA(1, 0, At, B0); PG8_MMA(1, 1, At, B1); PG8_BAR; PG8_SCHED;
;             } else {
;             PG8_LDB(B0, 0, 0); PG8_SCHED; PG8_LDA(At, 0, 0); PG8_STAGE(PG8_SA(1, 1), a1 + hstep, voffA);
;             PG8_WAIT_L(8); PG8_BAR; PG8_WAIT_L(0); PG8_MMA(0, 0, At, B0); PG8_BAR; PG8_SCHED;
;             PG8_LDB(B1, 0, 1); PG8_STAGE(PG8_SB(0, 0), b2, voffB);
;             PG8_BAR; PG8_WAIT_L(0); PG8_MMA(0, 1, At, B1); PG8_BAR;
;             PG8_LDA(At, 0, 1); PG8_STAGE(PG8_SA(0, 0), a2, voffA);
;             PG8_BAR; PG8_WAIT_L(0); PG8_MMA(1, 0, At, B0); PG8_BAR; PG8_SCHED;
;             PG8_STAGE(PG8_SB(0, 1), b2 + hstep, voffB);
;             PG8_WAIT_V(6); PG8_BAR; PG8_MMA(1, 1, At, B1); PG8_BAR;
;             PG8_LDB(B0, 1, 0); PG8_SCHED; PG8_LDA(At, 1, 0); PG8_STAGE(PG8_SA(0, 1), a2 + hstep, voffA);
;             PG8_WAIT_L(8); PG8_BAR; PG8_WAIT_L(0); PG8_MMA(0, 0, At, B0); PG8_BAR; PG8_SCHED;
;             PG8_LDB(B1, 1, 1); PG8_STAGE(PG8_SB(1, 0), b3, voffB);
;             PG8_BAR; PG8_WAIT_L(0); PG8_MMA(0, 1, At, B1); PG8_BAR;
;             PG8_LDA(At, 1, 1); PG8_STAGE(PG8_SA(1, 0), a3, voffA);
;             PG8_BAR; PG8_WAIT_L(0); PG8_MMA(1, 0, At, B0); PG8_BAR; PG8_SCHED;
;             PG8_STAGE(PG8_SB(1, 1), b3 + hstep, voffB);
;             PG8_WAIT_V(6); PG8_BAR; PG8_MMA(1, 1, At, B1); PG8_BAR;
;             }
;         }
;         if constexpr (ALIGN_EPI) { if (wr == 0) PG8_BAR; }
	v_mfma_f32_16x16x32_bf16 v[84:87], v[48:51], v[80:83], v[92:95]
	v_mfma_f32_16x16x32_bf16 v[92:95], v[52:55], v[206:209], v[84:87]
	v_mfma_f32_16x16x32_bf16 v[84:87], v[56:59], v[80:83], v[88:91]
	v_mfma_f32_16x16x32_bf16 v[76:79], v[48:51], v[210:213], v[76:79]
	v_mfma_f32_16x16x32_bf16 v[72:75], v[56:59], v[210:213], v[72:75]
	v_mfma_f32_16x16x32_bf16 v[28:31], v[48:51], v[218:221], v[28:31]
	v_mfma_f32_16x16x32_bf16 v[24:27], v[56:59], v[218:221], v[24:27]
	v_mfma_f32_16x16x32_bf16 v[12:15], v[48:51], v[226:229], v[12:15]
	v_mfma_f32_16x16x32_bf16 v[8:11], v[56:59], v[226:229], v[8:11]
	v_mfma_f32_16x16x32_bf16 v[88:91], v[60:63], v[206:209], v[84:87]
	v_mfma_f32_16x16x32_bf16 v[76:79], v[52:55], v[214:217], v[76:79]
	v_mfma_f32_16x16x32_bf16 v[72:75], v[60:63], v[214:217], v[72:75]
	v_mfma_f32_16x16x32_bf16 v[28:31], v[52:55], v[222:225], v[28:31]
	v_mfma_f32_16x16x32_bf16 v[24:27], v[60:63], v[222:225], v[24:27]
	v_mfma_f32_16x16x32_bf16 v[12:15], v[52:55], v[242:245], v[12:15]
	v_mfma_f32_16x16x32_bf16 v[8:11], v[60:63], v[242:245], v[8:11]
	s_setprio 0
	s_setprio 1
	v_mfma_f32_16x16x32_bf16 v[36:39], v[64:67], v[80:83], v[36:39]
	v_mfma_f32_16x16x32_bf16 v[84:87], v[68:71], v[206:209], v[36:39]
	v_mfma_f32_16x16x32_bf16 v[36:39], v[170:173], v[80:83], v[40:43]
	v_mfma_f32_16x16x32_bf16 v[80:83], v[174:177], v[206:209], v[36:39]
	v_mfma_f32_16x16x32_bf16 v[36:39], v[64:67], v[210:213], v[44:47]
	v_mfma_f32_16x16x32_bf16 v[32:35], v[170:173], v[210:213], v[32:35]
	v_mfma_f32_16x16x32_bf16 v[20:23], v[64:67], v[218:221], v[20:23]
	v_mfma_f32_16x16x32_bf16 v[16:19], v[170:173], v[218:221], v[16:19]
	v_mfma_f32_16x16x32_bf16 v[4:7], v[64:67], v[226:229], v[4:7]
	v_mfma_f32_16x16x32_bf16 v[0:3], v[170:173], v[226:229], v[0:3]
	v_mfma_f32_16x16x32_bf16 v[52:55], v[68:71], v[214:217], v[36:39]
	v_mfma_f32_16x16x32_bf16 v[32:35], v[174:177], v[214:217], v[32:35]
	v_mfma_f32_16x16x32_bf16 v[20:23], v[68:71], v[222:225], v[20:23]
	v_mfma_f32_16x16x32_bf16 v[16:19], v[174:177], v[222:225], v[16:19]
	v_mfma_f32_16x16x32_bf16 v[4:7], v[68:71], v[242:245], v[4:7]
	v_mfma_f32_16x16x32_bf16 v[0:3], v[174:177], v[242:245], v[0:3]
	s_barrier
	s_setprio 0
	s_add_i32 s49, s49, 2
	s_add_u32 s36, s36, 0x100
	s_addc_u32 s37, s37, 0
	s_add_u32 s27, s27, 0x100
	s_addc_u32 s29, s29, 0
	s_cmp_gt_u32 s49, 13
	s_cbranch_scc0 .LBB0_577
	s_and_b64 vcc, exec, s[24:25]
	s_cbranch_vccz .LBB0_580
	s_barrier

; #define PG8_STAGE(bufoff, gbase, voff) do { _Pragma("unroll") for (int _i = 0; _i < 2; ++_i) \
;         __builtin_amdgcn_global_load_lds((const unsigned*)((const char*)(gbase) + (voff)[_i]), (PG8_LAS unsigned*)(lds + (bufoff) + ldsw + _i * 8192), 16, 0, 0); } while (0)
; #define PG8_LDA(dst, b, h) do { _Pragma("unroll") for (int m = 0; m < 4; ++m) _Pragma("unroll") for (int k = 0; k < 2; ++k) dst[m][k] = *(const PG8_LAS bf16x8*)(lds + PG8_SA(b, h) + aoff + m * 2048 + k * 1024); } while (0)
; #define PG8_LDB(dst, b, h) do { _Pragma("unroll") for (int n = 0; n < 2; ++n) _Pragma("unroll") for (int k = 0; k < 2; ++k) dst[n][k] = *(const PG8_LAS bf16x8*)(lds + PG8_SB(b, h) + boff + n * 2048 + k * 1024); } while (0)
; #define PG8_MMA(ai, bj, At, Bt) do { __builtin_amdgcn_s_setprio(1); _Pragma("unroll") for (int m = 0; m < 4; ++m) _Pragma("unroll") for (int n = 0; n < 2; ++n) _Pragma("unroll") for (int k = 0; k < 2; ++k) \
;         acc[ai][bj][m][n] = __builtin_amdgcn_mfma_f32_16x16x32_bf16(Bt[n][k], At[m][k], acc[ai][bj][m][n], 0, 0, 0); __builtin_amdgcn_s_setprio(0); } while (0)
; #define PG8_WAIT_V(n) asm volatile("s_waitcnt vmcnt(" #n ")" ::: "memory")
; #define PG8_WAIT_L(n) asm volatile("s_waitcnt lgkmcnt(" #n ")" ::: "memory")
; #define PG8_BAR __builtin_amdgcn_s_barrier()
; template <class Epi, class Sched, bool ALIGN_EPI = false, bool SP2 = false>
; __device__ __forceinline__ void gemm_phase(PG8_LAS unsigned char* lds, const Gemm g, const Sched& S, const Epi& E) {
;     ...
;         const bool has_next = S.next(ui + 1, nxt);
;         const char* nA = has_next ? (const char*)g.A + (size_t)nxt.pm * tstep : cA; const char* nB = has_next ? (const char*)g.Bt + (size_t)nxt.pn * tstep : cB;
;         for (int t = 0; t < nt; t += 2) {
;             const bool last = (t == nt - 2);
;             const char* a1 = cA + (size_t)(t + 1) * kstep;
;             const char* a2 = last ? nA : cA + (size_t)(t + 2) * kstep; const char* b2 = last ? nB : cB + (size_t)(t + 2) * kstep;
;             const char* a3 = a2 + kstep; const char* b3 = b2 + kstep;
;             if (last && has_next) S.a_ready(nxt);
;             if constexpr (SP2) {
;             PG8_LDB(B0, 0, 0); PG8_LDB(B1, 0, 1); PG8_SCHED; PG8_LDA(At, 0, 0); PG8_STAGE(PG8_SA(1, 1), a1 + hstep, voffA);
;             PG8_WAIT_V(8); PG8_WAIT_L(0); PG8_BAR; PG8_MMA(0, 0, At, B0); PG8_MMA(0, 1, At, B1); PG8_BAR; PG8_SCHED;
.LBB0_666:
	s_add_u32 s78, s46, 0xfffc0080
	s_addc_u32 s79, s47, -1
	s_add_i32 vcc_lo, 0, 0x10000
	s_cmp_eq_u32 s75, 12
	s_cselect_b32 s95, s0, s79
	s_cselect_b32 s94, s1, s78
	s_cselect_b32 s79, s4, s57
	s_cselect_b32 s78, s5, s55
	s_add_i32 s76, 0, 0x14000
	v_add_u32_e32 v140, vcc_lo, v222
	v_add_u32_e32 v156, s76, v222
	ds_read_b128 v[72:75], v140
	ds_read_b128 v[132:135], v140 offset:1024
	ds_read_b128 v[136:139], v140 offset:2048
	ds_read_b128 v[140:143], v140 offset:3072
	ds_read_b128 v[144:147], v156
	ds_read_b128 v[148:151], v156 offset:1024
	ds_read_b128 v[152:155], v156 offset:2048
	ds_read_b128 v[156:159], v156 offset:3072
	v_lshl_add_u64 v[220:221], s[46:47], 0, v[206:207]
	s_add_i32 m0, s68, 0xc000
	ds_read_b128 v[160:163], v246
	ds_read_b128 v[164:167], v246 offset:1024
	ds_read_b128 v[168:171], v246 offset:2048
	ds_read_b128 v[172:175], v246 offset:3072
	ds_read_b128 v[176:179], v246 offset:4096
	ds_read_b128 v[180:183], v246 offset:5120
	ds_read_b128 v[212:215], v246 offset:6144
	ds_read_b128 v[216:219], v246 offset:7168
	global_load_lds_dwordx4 v[220:221], off
	v_lshl_add_u64 v[220:221], s[46:47], 0, v[208:209]
	s_add_i32 m0, s68, 0xe000
	s_nop 0
	global_load_lds_dwordx4 v[220:221], off
	s_waitcnt vmcnt(8)
	s_waitcnt lgkmcnt(0)
	s_setprio 1
	s_barrier

; #define PG8_STAGE(bufoff, gbase, voff) do { _Pragma("unroll") for (int _i = 0; _i < 2; ++_i) \
;         __builtin_amdgcn_global_load_lds((const unsigned*)((const char*)(gbase) + (voff)[_i]), (PG8_LAS unsigned*)(lds + (bufoff) + ldsw + _i * 8192), 16, 0, 0); } while (0)
; #define PG8_LDA(dst, b, h) do { _Pragma("unroll") for (int m = 0; m < 4; ++m) _Pragma("unroll") for (int k = 0; k < 2; ++k) dst[m][k] = *(const PG8_LAS bf16x8*)(lds + PG8_SA(b, h) + aoff + m * 2048 + k * 1024); } while (0)
; #define PG8_MMA(ai, bj, At, Bt) do { __builtin_amdgcn_s_setprio(1); _Pragma("unroll") for (int m = 0; m < 4; ++m) _Pragma("unroll") for (int n = 0; n < 2; ++n) _Pragma("unroll") for (int k = 0; k < 2; ++k) \
;         acc[ai][bj][m][n] = __builtin_amdgcn_mfma_f32_16x16x32_bf16(Bt[n][k], At[m][k], acc[ai][bj][m][n], 0, 0, 0); __builtin_amdgcn_s_setprio(0); } while (0)
; #define PG8_WAIT_V(n) asm volatile("s_waitcnt vmcnt(" #n ")" ::: "memory")
; #define PG8_WAIT_L(n) asm volatile("s_waitcnt lgkmcnt(" #n ")" ::: "memory")
; #define PG8_BAR __builtin_amdgcn_s_barrier()
; #define PG8_SCHED __builtin_amdgcn_sched_barrier(0)
; template <class Epi, class Sched, bool ALIGN_EPI = false, bool SP2 = false>
; __device__ __forceinline__ void gemm_phase(PG8_LAS unsigned char* lds, const Gemm g, const Sched& S, const Epi& E) {
;     ...
;             PG8_WAIT_V(8); PG8_WAIT_L(0); PG8_BAR; PG8_MMA(0, 0, At, B0); PG8_MMA(0, 1, At, B1); PG8_BAR; PG8_SCHED;
;             PG8_LDA(At, 0, 1); PG8_STAGE(PG8_SB(0, 0), b2, voffB); PG8_STAGE(PG8_SB(0, 1), b2 + hstep, voffB); PG8_STAGE(PG8_SA(0, 0), a2, voffA);
;             PG8_WAIT_V(8); PG8_WAIT_L(0); PG8_BAR; PG8_MMA(1, 0, At, B0); PG8_MMA(1, 1, At, B1); PG8_BAR; PG8_SCHED;
	v_mfma_f32_16x16x32_bf16 v[48:51], v[72:75], v[160:163], v[48:51]
	v_mfma_f32_16x16x32_bf16 v[128:131], v[136:139], v[160:163], v[128:131]
	v_mfma_f32_16x16x32_bf16 v[124:127], v[72:75], v[168:171], v[124:127]
	v_mfma_f32_16x16x32_bf16 v[116:119], v[136:139], v[168:171], v[116:119]
	v_mfma_f32_16x16x32_bf16 v[120:123], v[72:75], v[176:179], v[120:123]
	v_mfma_f32_16x16x32_bf16 v[112:115], v[136:139], v[176:179], v[112:115]
	v_mfma_f32_16x16x32_bf16 v[24:27], v[72:75], v[212:215], v[24:27]
	v_mfma_f32_16x16x32_bf16 v[16:19], v[136:139], v[212:215], v[16:19]
	v_mfma_f32_16x16x32_bf16 v[48:51], v[132:135], v[164:167], v[48:51]
	v_mfma_f32_16x16x32_bf16 v[128:131], v[140:143], v[164:167], v[128:131]
	v_mfma_f32_16x16x32_bf16 v[124:127], v[132:135], v[172:175], v[124:127]
	v_mfma_f32_16x16x32_bf16 v[116:119], v[140:143], v[172:175], v[116:119]
	v_mfma_f32_16x16x32_bf16 v[120:123], v[132:135], v[180:183], v[120:123]
	v_mfma_f32_16x16x32_bf16 v[112:115], v[140:143], v[180:183], v[112:115]
	v_mfma_f32_16x16x32_bf16 v[24:27], v[132:135], v[216:219], v[24:27]
	v_mfma_f32_16x16x32_bf16 v[16:19], v[140:143], v[216:219], v[16:19]
	s_setprio 0
	s_setprio 1
	v_mfma_f32_16x16x32_bf16 v[76:79], v[144:147], v[160:163], v[76:79]
	v_mfma_f32_16x16x32_bf16 v[28:31], v[152:155], v[160:163], v[28:31]
	v_mfma_f32_16x16x32_bf16 v[104:107], v[144:147], v[168:171], v[104:107]
	v_mfma_f32_16x16x32_bf16 v[88:91], v[152:155], v[168:171], v[88:91]
	v_mfma_f32_16x16x32_bf16 v[96:99], v[144:147], v[176:179], v[96:99]
	v_mfma_f32_16x16x32_bf16 v[80:83], v[152:155], v[176:179], v[80:83]
	v_mfma_f32_16x16x32_bf16 v[52:55], v[144:147], v[212:215], v[52:55]
	v_mfma_f32_16x16x32_bf16 v[20:23], v[152:155], v[212:215], v[20:23]
	v_mfma_f32_16x16x32_bf16 v[76:79], v[148:151], v[164:167], v[76:79]
	v_mfma_f32_16x16x32_bf16 v[28:31], v[156:159], v[164:167], v[28:31]
	v_mfma_f32_16x16x32_bf16 v[104:107], v[148:151], v[172:175], v[104:107]
	v_mfma_f32_16x16x32_bf16 v[88:91], v[156:159], v[172:175], v[88:91]
	v_mfma_f32_16x16x32_bf16 v[96:99], v[148:151], v[180:183], v[96:99]
	v_mfma_f32_16x16x32_bf16 v[80:83], v[156:159], v[180:183], v[80:83]
	v_mfma_f32_16x16x32_bf16 v[52:55], v[148:151], v[216:219], v[52:55]
	v_mfma_f32_16x16x32_bf16 v[20:23], v[156:159], v[216:219], v[20:23]
	s_barrier
	s_setprio 0
	s_add_i32 s77, vcc_lo, s64
	v_lshl_add_u64 v[220:221], s[78:79], 0, v[194:195]
	s_mov_b32 m0, s77
	ds_read_b128 v[160:163], v246 offset:16384
	ds_read_b128 v[164:167], v246 offset:17408
	ds_read_b128 v[168:171], v246 offset:18432
	ds_read_b128 v[172:175], v246 offset:19456
	ds_read_b128 v[176:179], v246 offset:20480
	ds_read_b128 v[180:183], v246 offset:21504
	ds_read_b128 v[212:215], v246 offset:22528
	ds_read_b128 v[216:219], v246 offset:23552
	global_load_lds_dwordx4 v[220:221], off
	s_add_i32 m0, s77, 0x2000
	s_add_u32 vcc_lo, s78, 0x40000
	v_lshl_add_u64 v[238:239], s[78:79], 0, v[184:185]
	s_addc_u32 vcc_hi, s79, 0
	s_add_i32 s76, s76, s64
	global_load_lds_dwordx4 v[238:239], off
	v_lshl_add_u64 v[240:241], vcc, 0, v[194:195]
	s_mov_b32 m0, s76
	v_lshl_add_u64 v[248:249], s[94:95], 0, v[186:187]
	global_load_lds_dwordx4 v[240:241], off
	v_lshl_add_u64 v[240:241], vcc, 0, v[184:185]
	s_add_i32 m0, s76, 0x2000
	s_nop 0
	global_load_lds_dwordx4 v[240:241], off
	v_lshl_add_u64 v[240:241], s[94:95], 0, v[196:197]
	s_mov_b32 m0, s68
	s_nop 0
	global_load_lds_dwordx4 v[240:241], off
	s_mov_b32 m0, s69
	s_nop 0
	global_load_lds_dwordx4 v[248:249], off
	s_waitcnt vmcnt(8)
	s_waitcnt lgkmcnt(0)
	s_setprio 1
	s_barrier

; #define PG8_STAGE(bufoff, gbase, voff) do { _Pragma("unroll") for (int _i = 0; _i < 2; ++_i) \
;         __builtin_amdgcn_global_load_lds((const unsigned*)((const char*)(gbase) + (voff)[_i]), (PG8_LAS unsigned*)(lds + (bufoff) + ldsw + _i * 8192), 16, 0, 0); } while (0)
; #define PG8_LDA(dst, b, h) do { _Pragma("unroll") for (int m = 0; m < 4; ++m) _Pragma("unroll") for (int k = 0; k < 2; ++k) dst[m][k] = *(const PG8_LAS bf16x8*)(lds + PG8_SA(b, h) + aoff + m * 2048 + k * 1024); } while (0)
; #define PG8_LDB(dst, b, h) do { _Pragma("unroll") for (int n = 0; n < 2; ++n) _Pragma("unroll") for (int k = 0; k < 2; ++k) dst[n][k] = *(const PG8_LAS bf16x8*)(lds + PG8_SB(b, h) + boff + n * 2048 + k * 1024); } while (0)
; #define PG8_MMA(ai, bj, At, Bt) do { __builtin_amdgcn_s_setprio(1); _Pragma("unroll") for (int m = 0; m < 4; ++m) _Pragma("unroll") for (int n = 0; n < 2; ++n) _Pragma("unroll") for (int k = 0; k < 2; ++k) \
;         acc[ai][bj][m][n] = __builtin_amdgcn_mfma_f32_16x16x32_bf16(Bt[n][k], At[m][k], acc[ai][bj][m][n], 0, 0, 0); __builtin_amdgcn_s_setprio(0); } while (0)
; #define PG8_WAIT_V(n) asm volatile("s_waitcnt vmcnt(" #n ")" ::: "memory")
; #define PG8_WAIT_L(n) asm volatile("s_waitcnt lgkmcnt(" #n ")" ::: "memory")
; #define PG8_BAR __builtin_amdgcn_s_barrier()
; #define PG8_SCHED __builtin_amdgcn_sched_barrier(0)
; template <class Epi, class Sched, bool ALIGN_EPI = false, bool SP2 = false>
; __device__ __forceinline__ void gemm_phase(PG8_LAS unsigned char* lds, const Gemm g, const Sched& S, const Epi& E) {
;     ...
;             PG8_WAIT_V(8); PG8_WAIT_L(0); PG8_BAR; PG8_MMA(1, 0, At, B0); PG8_MMA(1, 1, At, B1); PG8_BAR; PG8_SCHED;
;             PG8_LDB(B0, 1, 0); PG8_LDB(B1, 1, 1); PG8_SCHED; PG8_LDA(At, 1, 0); PG8_STAGE(PG8_SA(0, 1), a2 + hstep, voffA);
;             PG8_WAIT_V(8); PG8_WAIT_L(0); PG8_BAR; PG8_MMA(0, 0, At, B0); PG8_MMA(0, 1, At, B1); PG8_BAR; PG8_SCHED;
	v_mfma_f32_16x16x32_bf16 v[40:43], v[72:75], v[160:163], v[40:43]
	v_mfma_f32_16x16x32_bf16 v[8:11], v[136:139], v[160:163], v[8:11]
	v_mfma_f32_16x16x32_bf16 v[108:111], v[72:75], v[168:171], v[108:111]
	v_mfma_f32_16x16x32_bf16 v[92:95], v[136:139], v[168:171], v[92:95]
	v_mfma_f32_16x16x32_bf16 v[100:103], v[72:75], v[176:179], v[100:103]
	v_mfma_f32_16x16x32_bf16 v[84:87], v[136:139], v[176:179], v[84:87]
	v_mfma_f32_16x16x32_bf16 v[32:35], v[72:75], v[212:215], v[32:35]
	v_mfma_f32_16x16x32_bf16 v[0:3], v[136:139], v[212:215], v[0:3]
	v_mfma_f32_16x16x32_bf16 v[40:43], v[132:135], v[164:167], v[40:43]
	v_mfma_f32_16x16x32_bf16 v[8:11], v[140:143], v[164:167], v[8:11]
	v_mfma_f32_16x16x32_bf16 v[108:111], v[132:135], v[172:175], v[108:111]
	v_mfma_f32_16x16x32_bf16 v[92:95], v[140:143], v[172:175], v[92:95]
	v_mfma_f32_16x16x32_bf16 v[100:103], v[132:135], v[180:183], v[100:103]
	v_mfma_f32_16x16x32_bf16 v[84:87], v[140:143], v[180:183], v[84:87]
	v_mfma_f32_16x16x32_bf16 v[32:35], v[132:135], v[216:219], v[32:35]
	v_mfma_f32_16x16x32_bf16 v[0:3], v[140:143], v[216:219], v[0:3]
	s_setprio 0
	s_setprio 1
	v_mfma_f32_16x16x32_bf16 v[44:47], v[144:147], v[160:163], v[44:47]
	v_mfma_f32_16x16x32_bf16 v[12:15], v[152:155], v[160:163], v[12:15]
	v_mfma_f32_16x16x32_bf16 v[68:71], v[144:147], v[168:171], v[68:71]
	v_mfma_f32_16x16x32_bf16 v[60:63], v[152:155], v[168:171], v[60:63]
	v_mfma_f32_16x16x32_bf16 v[64:67], v[144:147], v[176:179], v[64:67]
	v_mfma_f32_16x16x32_bf16 v[56:59], v[152:155], v[176:179], v[56:59]
	v_mfma_f32_16x16x32_bf16 v[36:39], v[144:147], v[212:215], v[36:39]
	v_mfma_f32_16x16x32_bf16 v[4:7], v[152:155], v[212:215], v[4:7]
	v_mfma_f32_16x16x32_bf16 v[44:47], v[148:151], v[164:167], v[44:47]
	v_mfma_f32_16x16x32_bf16 v[12:15], v[156:159], v[164:167], v[12:15]
	v_mfma_f32_16x16x32_bf16 v[68:71], v[148:151], v[172:175], v[68:71]
	v_mfma_f32_16x16x32_bf16 v[60:63], v[156:159], v[172:175], v[60:63]
	v_mfma_f32_16x16x32_bf16 v[64:67], v[148:151], v[180:183], v[64:67]
	v_mfma_f32_16x16x32_bf16 v[56:59], v[156:159], v[180:183], v[56:59]
	v_mfma_f32_16x16x32_bf16 v[36:39], v[148:151], v[216:219], v[36:39]
	v_mfma_f32_16x16x32_bf16 v[4:7], v[156:159], v[216:219], v[4:7]
	s_barrier
	s_setprio 0
	s_add_i32 s76, 0, 0x18000
	s_add_i32 s77, 0, 0x1c000
	v_add_u32_e32 v140, s76, v222
	v_add_u32_e32 v156, s77, v222
	ds_read_b128 v[72:75], v140
	ds_read_b128 v[132:135], v140 offset:1024
	ds_read_b128 v[136:139], v140 offset:2048
	ds_read_b128 v[140:143], v140 offset:3072
	ds_read_b128 v[144:147], v156
	ds_read_b128 v[148:151], v156 offset:1024
	ds_read_b128 v[152:155], v156 offset:2048
	ds_read_b128 v[156:159], v156 offset:3072
	s_add_u32 s94, s94, 0x40000
	s_addc_u32 s95, s95, 0
	s_mov_b32 m0, s70
	v_lshl_add_u64 v[250:251], s[94:95], 0, v[196:197]
	ds_read_b128 v[160:163], v246 offset:32768
	ds_read_b128 v[164:167], v246 offset:33792
	ds_read_b128 v[168:171], v246 offset:34816
	ds_read_b128 v[172:175], v246 offset:35840
	ds_read_b128 v[176:179], v246 offset:36864
	ds_read_b128 v[180:183], v246 offset:37888
	ds_read_b128 v[212:215], v246 offset:38912
	ds_read_b128 v[216:219], v246 offset:39936
	global_load_lds_dwordx4 v[250:251], off
	v_lshl_add_u64 v[250:251], s[94:95], 0, v[186:187]
	s_mov_b32 m0, s71
	s_nop 0
	global_load_lds_dwordx4 v[250:251], off
	s_waitcnt vmcnt(8)
	s_waitcnt lgkmcnt(0)
	s_setprio 1
	s_barrier

; #define PG8_STAGE(bufoff, gbase, voff) do { _Pragma("unroll") for (int _i = 0; _i < 2; ++_i) \
;         __builtin_amdgcn_global_load_lds((const unsigned*)((const char*)(gbase) + (voff)[_i]), (PG8_LAS unsigned*)(lds + (bufoff) + ldsw + _i * 8192), 16, 0, 0); } while (0)
; #define PG8_LDA(dst, b, h) do { _Pragma("unroll") for (int m = 0; m < 4; ++m) _Pragma("unroll") for (int k = 0; k < 2; ++k) dst[m][k] = *(const PG8_LAS bf16x8*)(lds + PG8_SA(b, h) + aoff + m * 2048 + k * 1024); } while (0)
; #define PG8_MMA(ai, bj, At, Bt) do { __builtin_amdgcn_s_setprio(1); _Pragma("unroll") for (int m = 0; m < 4; ++m) _Pragma("unroll") for (int n = 0; n < 2; ++n) _Pragma("unroll") for (int k = 0; k < 2; ++k) \
;         acc[ai][bj][m][n] = __builtin_amdgcn_mfma_f32_16x16x32_bf16(Bt[n][k], At[m][k], acc[ai][bj][m][n], 0, 0, 0); __builtin_amdgcn_s_setprio(0); } while (0)
; #define PG8_WAIT_V(n) asm volatile("s_waitcnt vmcnt(" #n ")" ::: "memory")
; #define PG8_WAIT_L(n) asm volatile("s_waitcnt lgkmcnt(" #n ")" ::: "memory")
; #define PG8_BAR __builtin_amdgcn_s_barrier()
; #define PG8_SCHED __builtin_amdgcn_sched_barrier(0)
; template <class Epi, class Sched, bool ALIGN_EPI = false, bool SP2 = false>
; __device__ __forceinline__ void gemm_phase(PG8_LAS unsigned char* lds, const Gemm g, const Sched& S, const Epi& E) {
;     ...
;             PG8_WAIT_V(8); PG8_WAIT_L(0); PG8_BAR; PG8_MMA(0, 0, At, B0); PG8_MMA(0, 1, At, B1); PG8_BAR; PG8_SCHED;
;             PG8_LDA(At, 1, 1); PG8_STAGE(PG8_SB(1, 0), b3, voffB); PG8_STAGE(PG8_SB(1, 1), b3 + hstep, voffB); PG8_STAGE(PG8_SA(1, 0), a3, voffA);
;             PG8_WAIT_V(8); PG8_WAIT_L(0); PG8_BAR; PG8_MMA(1, 0, At, B0); PG8_MMA(1, 1, At, B1); PG8_BAR; PG8_SCHED;
	v_mfma_f32_16x16x32_bf16 v[48:51], v[72:75], v[160:163], v[48:51]
	v_mfma_f32_16x16x32_bf16 v[128:131], v[136:139], v[160:163], v[128:131]
	v_mfma_f32_16x16x32_bf16 v[124:127], v[72:75], v[168:171], v[124:127]
	v_mfma_f32_16x16x32_bf16 v[116:119], v[136:139], v[168:171], v[116:119]
	v_mfma_f32_16x16x32_bf16 v[120:123], v[72:75], v[176:179], v[120:123]
	v_mfma_f32_16x16x32_bf16 v[112:115], v[136:139], v[176:179], v[112:115]
	v_mfma_f32_16x16x32_bf16 v[24:27], v[72:75], v[212:215], v[24:27]
	v_mfma_f32_16x16x32_bf16 v[16:19], v[136:139], v[212:215], v[16:19]
	v_mfma_f32_16x16x32_bf16 v[48:51], v[132:135], v[164:167], v[48:51]
	v_mfma_f32_16x16x32_bf16 v[128:131], v[140:143], v[164:167], v[128:131]
	v_mfma_f32_16x16x32_bf16 v[124:127], v[132:135], v[172:175], v[124:127]
	v_mfma_f32_16x16x32_bf16 v[116:119], v[140:143], v[172:175], v[116:119]
	v_mfma_f32_16x16x32_bf16 v[120:123], v[132:135], v[180:183], v[120:123]
	v_mfma_f32_16x16x32_bf16 v[112:115], v[140:143], v[180:183], v[112:115]
	v_mfma_f32_16x16x32_bf16 v[24:27], v[132:135], v[216:219], v[24:27]
	v_mfma_f32_16x16x32_bf16 v[16:19], v[140:143], v[216:219], v[16:19]
	s_setprio 0
	s_setprio 1
	v_mfma_f32_16x16x32_bf16 v[76:79], v[144:147], v[160:163], v[76:79]
	v_mfma_f32_16x16x32_bf16 v[28:31], v[152:155], v[160:163], v[28:31]
	v_mfma_f32_16x16x32_bf16 v[104:107], v[144:147], v[168:171], v[104:107]
	v_mfma_f32_16x16x32_bf16 v[88:91], v[152:155], v[168:171], v[88:91]
	v_mfma_f32_16x16x32_bf16 v[96:99], v[144:147], v[176:179], v[96:99]
	v_mfma_f32_16x16x32_bf16 v[80:83], v[152:155], v[176:179], v[80:83]
	v_mfma_f32_16x16x32_bf16 v[52:55], v[144:147], v[212:215], v[52:55]
	v_mfma_f32_16x16x32_bf16 v[20:23], v[152:155], v[212:215], v[20:23]
	v_mfma_f32_16x16x32_bf16 v[76:79], v[148:151], v[164:167], v[76:79]
	v_mfma_f32_16x16x32_bf16 v[28:31], v[156:159], v[164:167], v[28:31]
	v_mfma_f32_16x16x32_bf16 v[104:107], v[148:151], v[172:175], v[104:107]
	v_mfma_f32_16x16x32_bf16 v[88:91], v[156:159], v[172:175], v[88:91]
	v_mfma_f32_16x16x32_bf16 v[96:99], v[148:151], v[180:183], v[96:99]
	v_mfma_f32_16x16x32_bf16 v[80:83], v[156:159], v[180:183], v[80:83]
	v_mfma_f32_16x16x32_bf16 v[52:55], v[148:151], v[216:219], v[52:55]
	v_mfma_f32_16x16x32_bf16 v[20:23], v[156:159], v[216:219], v[20:23]
	s_barrier
	s_setprio 0
	s_add_i32 s76, s76, s64
	v_lshl_add_u64 v[220:221], v[220:221], 0, s[90:91]
	s_mov_b32 m0, s76
	ds_read_b128 v[160:163], v246 offset:49152
	ds_read_b128 v[164:167], v246 offset:50176
	ds_read_b128 v[168:171], v246 offset:51200
	ds_read_b128 v[172:175], v246 offset:52224
	ds_read_b128 v[176:179], v246 offset:53248
	ds_read_b128 v[180:183], v246 offset:54272
	ds_read_b128 v[212:215], v246 offset:55296
	ds_read_b128 v[216:219], v246 offset:56320
	global_load_lds_dwordx4 v[220:221], off
	s_add_i32 m0, s76, 0x2000
	s_add_u32 s78, s78, 0x40080
	v_lshl_add_u64 v[220:221], v[238:239], 0, s[90:91]
	s_addc_u32 s79, s79, 0
	s_add_i32 s76, s77, s64
	global_load_lds_dwordx4 v[220:221], off
	v_lshl_add_u64 v[220:221], s[78:79], 0, v[194:195]
	s_mov_b32 m0, s76
	s_nop 0
	global_load_lds_dwordx4 v[220:221], off
	v_lshl_add_u64 v[220:221], s[78:79], 0, v[184:185]
	s_add_i32 m0, s76, 0x2000
	s_nop 0
	global_load_lds_dwordx4 v[220:221], off
	v_lshl_add_u64 v[220:221], v[240:241], 0, s[90:91]
	s_mov_b32 m0, s89
	s_nop 0
	global_load_lds_dwordx4 v[220:221], off
	v_lshl_add_u64 v[220:221], v[248:249], 0, s[90:91]
	s_mov_b32 m0, s92
	s_nop 0
	global_load_lds_dwordx4 v[220:221], off
	s_waitcnt vmcnt(8)
	s_waitcnt lgkmcnt(0)
	s_setprio 1
	s_barrier

; #define PG8_STAGE(bufoff, gbase, voff) do { _Pragma("unroll") for (int _i = 0; _i < 2; ++_i) \
;         __builtin_amdgcn_global_load_lds((const unsigned*)((const char*)(gbase) + (voff)[_i]), (PG8_LAS unsigned*)(lds + (bufoff) + ldsw + _i * 8192), 16, 0, 0); } while (0)
; #define PG8_LDA(dst, b, h) do { _Pragma("unroll") for (int m = 0; m < 4; ++m) _Pragma("unroll") for (int k = 0; k < 2; ++k) dst[m][k] = *(const PG8_LAS bf16x8*)(lds + PG8_SA(b, h) + aoff + m * 2048 + k * 1024); } while (0)
; #define PG8_LDB(dst, b, h) do { _Pragma("unroll") for (int n = 0; n < 2; ++n) _Pragma("unroll") for (int k = 0; k < 2; ++k) dst[n][k] = *(const PG8_LAS bf16x8*)(lds + PG8_SB(b, h) + boff + n * 2048 + k * 1024); } while (0)
; template <class Epi, class Sched, bool ALIGN_EPI = false, bool SP2 = false>
; __device__ __forceinline__ void gemm_phase(PG8_LAS unsigned char* lds, const Gemm g, const Sched& S, const Epi& E) {
;     ...
;             PG8_WAIT_V(8); PG8_WAIT_L(0); PG8_BAR; PG8_MMA(1, 0, At, B0); PG8_MMA(1, 1, At, B1); PG8_BAR; PG8_SCHED;
;             } else {
;             PG8_LDB(B0, 0, 0); PG8_SCHED; PG8_LDA(At, 0, 0); PG8_STAGE(PG8_SA(1, 1), a1 + hstep, voffA);
;             PG8_WAIT_L(8); PG8_BAR; PG8_WAIT_L(0); PG8_MMA(0, 0, At, B0); PG8_BAR; PG8_SCHED;
;             PG8_LDB(B1, 0, 1); PG8_STAGE(PG8_SB(0, 0), b2, voffB);
;             PG8_BAR; PG8_WAIT_L(0); PG8_MMA(0, 1, At, B1); PG8_BAR;
;             PG8_LDA(At, 0, 1); PG8_STAGE(PG8_SA(0, 0), a2, voffA);
;             PG8_BAR; PG8_WAIT_L(0); PG8_MMA(1, 0, At, B0); PG8_BAR; PG8_SCHED;
;             PG8_STAGE(PG8_SB(0, 1), b2 + hstep, voffB);
;             PG8_WAIT_V(6); PG8_BAR; PG8_MMA(1, 1, At, B1); PG8_BAR;
;             PG8_LDB(B0, 1, 0); PG8_SCHED; PG8_LDA(At, 1, 0); PG8_STAGE(PG8_SA(0, 1), a2 + hstep, voffA);
;             PG8_WAIT_L(8); PG8_BAR; PG8_WAIT_L(0); PG8_MMA(0, 0, At, B0); PG8_BAR; PG8_SCHED;
;             PG8_LDB(B1, 1, 1); PG8_STAGE(PG8_SB(1, 0), b3, voffB);
;             PG8_BAR; PG8_WAIT_L(0); PG8_MMA(0, 1, At, B1); PG8_BAR;
;             PG8_LDA(At, 1, 1); PG8_STAGE(PG8_SA(1, 0), a3, voffA);
;             PG8_BAR; PG8_WAIT_L(0); PG8_MMA(1, 0, At, B0); PG8_BAR; PG8_SCHED;
;             PG8_STAGE(PG8_SB(1, 1), b3 + hstep, voffB);
;             PG8_WAIT_V(6); PG8_BAR; PG8_MMA(1, 1, At, B1); PG8_BAR;
;             }
;         }
;         if constexpr (ALIGN_EPI) { if (wr == 0) PG8_BAR; }
	v_mfma_f32_16x16x32_bf16 v[40:43], v[72:75], v[160:163], v[40:43]
	v_mfma_f32_16x16x32_bf16 v[8:11], v[136:139], v[160:163], v[8:11]
	v_mfma_f32_16x16x32_bf16 v[108:111], v[72:75], v[168:171], v[108:111]
	v_mfma_f32_16x16x32_bf16 v[92:95], v[136:139], v[168:171], v[92:95]
	v_mfma_f32_16x16x32_bf16 v[100:103], v[72:75], v[176:179], v[100:103]
	v_mfma_f32_16x16x32_bf16 v[84:87], v[136:139], v[176:179], v[84:87]
	v_mfma_f32_16x16x32_bf16 v[32:35], v[72:75], v[212:215], v[32:35]
	v_mfma_f32_16x16x32_bf16 v[0:3], v[136:139], v[212:215], v[0:3]
	v_mfma_f32_16x16x32_bf16 v[40:43], v[132:135], v[164:167], v[40:43]
	v_mfma_f32_16x16x32_bf16 v[8:11], v[140:143], v[164:167], v[8:11]
	v_mfma_f32_16x16x32_bf16 v[108:111], v[132:135], v[172:175], v[108:111]
	v_mfma_f32_16x16x32_bf16 v[92:95], v[140:143], v[172:175], v[92:95]
	v_mfma_f32_16x16x32_bf16 v[100:103], v[132:135], v[180:183], v[100:103]
	v_mfma_f32_16x16x32_bf16 v[84:87], v[140:143], v[180:183], v[84:87]
	v_mfma_f32_16x16x32_bf16 v[32:35], v[132:135], v[216:219], v[32:35]
	v_mfma_f32_16x16x32_bf16 v[0:3], v[140:143], v[216:219], v[0:3]
	s_setprio 0
	s_setprio 1
	v_mfma_f32_16x16x32_bf16 v[44:47], v[144:147], v[160:163], v[44:47]
	v_mfma_f32_16x16x32_bf16 v[12:15], v[152:155], v[160:163], v[12:15]
	v_mfma_f32_16x16x32_bf16 v[68:71], v[144:147], v[168:171], v[68:71]
	v_mfma_f32_16x16x32_bf16 v[60:63], v[152:155], v[168:171], v[60:63]
	v_mfma_f32_16x16x32_bf16 v[64:67], v[144:147], v[176:179], v[64:67]
	v_mfma_f32_16x16x32_bf16 v[56:59], v[152:155], v[176:179], v[56:59]
	v_mfma_f32_16x16x32_bf16 v[36:39], v[144:147], v[212:215], v[36:39]
	v_mfma_f32_16x16x32_bf16 v[4:7], v[152:155], v[212:215], v[4:7]
	v_mfma_f32_16x16x32_bf16 v[44:47], v[148:151], v[164:167], v[44:47]
	v_mfma_f32_16x16x32_bf16 v[12:15], v[156:159], v[164:167], v[12:15]
	v_mfma_f32_16x16x32_bf16 v[68:71], v[148:151], v[172:175], v[68:71]
	v_mfma_f32_16x16x32_bf16 v[60:63], v[156:159], v[172:175], v[60:63]
	v_mfma_f32_16x16x32_bf16 v[64:67], v[148:151], v[180:183], v[64:67]
	v_mfma_f32_16x16x32_bf16 v[56:59], v[156:159], v[180:183], v[56:59]
	v_mfma_f32_16x16x32_bf16 v[36:39], v[148:151], v[216:219], v[36:39]
	v_mfma_f32_16x16x32_bf16 v[4:7], v[156:159], v[216:219], v[4:7]
	s_barrier
	s_setprio 0
	s_add_i32 s75, s75, 2
	s_add_u32 s46, s46, 0x100
	s_addc_u32 s47, s47, 0
	s_add_u32 s55, s55, 0x100
	s_addc_u32 s57, s57, 0
	s_cmp_gt_u32 s75, 13
	s_cbranch_scc0 .LBB0_666
	s_and_b64 vcc, exec, s[26:27]
	s_cbranch_vccz .LBB0_669
	s_barrier

; #define PG8_STAGE(bufoff, gbase, voff) do { _Pragma("unroll") for (int _i = 0; _i < 2; ++_i) \
;         __builtin_amdgcn_global_load_lds((const unsigned*)((const char*)(gbase) + (voff)[_i]), (PG8_LAS unsigned*)(lds + (bufoff) + ldsw + _i * 8192), 16, 0, 0); } while (0)
; #define PG8_LDA(dst, b, h) do { _Pragma("unroll") for (int m = 0; m < 4; ++m) _Pragma("unroll") for (int k = 0; k < 2; ++k) dst[m][k] = *(const PG8_LAS bf16x8*)(lds + PG8_SA(b, h) + aoff + m * 2048 + k * 1024); } while (0)
; #define PG8_LDB(dst, b, h) do { _Pragma("unroll") for (int n = 0; n < 2; ++n) _Pragma("unroll") for (int k = 0; k < 2; ++k) dst[n][k] = *(const PG8_LAS bf16x8*)(lds + PG8_SB(b, h) + boff + n * 2048 + k * 1024); } while (0)
; #define PG8_MMA(ai, bj, At, Bt) do { __builtin_amdgcn_s_setprio(1); _Pragma("unroll") for (int m = 0; m < 4; ++m) _Pragma("unroll") for (int n = 0; n < 2; ++n) _Pragma("unroll") for (int k = 0; k < 2; ++k) \
;         acc[ai][bj][m][n] = __builtin_amdgcn_mfma_f32_16x16x32_bf16(Bt[n][k], At[m][k], acc[ai][bj][m][n], 0, 0, 0); __builtin_amdgcn_s_setprio(0); } while (0)
; #define PG8_WAIT_V(n) asm volatile("s_waitcnt vmcnt(" #n ")" ::: "memory")
; #define PG8_WAIT_L(n) asm volatile("s_waitcnt lgkmcnt(" #n ")" ::: "memory")
; #define PG8_BAR __builtin_amdgcn_s_barrier()
; template <class Epi, class Sched, bool ALIGN_EPI = false, bool SP2 = false>
; __device__ __forceinline__ void gemm_phase(PG8_LAS unsigned char* lds, const Gemm g, const Sched& S, const Epi& E) {
;     ...
;         const bool has_next = S.next(ui + 1, nxt);
;         const char* nA = has_next ? (const char*)g.A + (size_t)nxt.pm * tstep : cA; const char* nB = has_next ? (const char*)g.Bt + (size_t)nxt.pn * tstep : cB;
;         for (int t = 0; t < nt; t += 2) {
;             const bool last = (t == nt - 2);
;             const char* a1 = cA + (size_t)(t + 1) * kstep;
;             const char* a2 = last ? nA : cA + (size_t)(t + 2) * kstep; const char* b2 = last ? nB : cB + (size_t)(t + 2) * kstep;
;             const char* a3 = a2 + kstep; const char* b3 = b2 + kstep;
;             if (last && has_next) S.a_ready(nxt);
;             if constexpr (SP2) {
;             PG8_LDB(B0, 0, 0); PG8_LDB(B1, 0, 1); PG8_SCHED; PG8_LDA(At, 0, 0); PG8_STAGE(PG8_SA(1, 1), a1 + hstep, voffA);
;             PG8_WAIT_V(8); PG8_WAIT_L(0); PG8_BAR; PG8_MMA(0, 0, At, B0); PG8_MMA(0, 1, At, B1); PG8_BAR; PG8_SCHED;
.LBB0_832:
	s_add_u32 s38, s36, 0x100
	s_addc_u32 s39, s37, 0
	s_add_i32 s5, 0, 0x10000
	s_cmp_eq_u32 s4, 40
	s_cselect_b32 s49, s31, s39
	s_cselect_b32 s48, s30, s38
	s_cselect_b32 s47, s35, s1
	s_cselect_b32 s46, s34, s0
	s_add_i32 s74, 0, 0x14000
	v_add_u32_e32 v68, s5, v199
	v_add_u32_e32 v92, s74, v199
	ds_read_b128 v[56:59], v68
	ds_read_b128 v[60:63], v68 offset:1024
	ds_read_b128 v[64:67], v68 offset:2048
	ds_read_b128 v[68:71], v68 offset:3072
	ds_read_b128 v[76:79], v92
	ds_read_b128 v[80:83], v92 offset:1024
	ds_read_b128 v[88:91], v92 offset:2048
	ds_read_b128 v[92:95], v92 offset:3072
	v_lshl_add_u64 v[186:187], s[36:37], 0, v[170:171]
	s_add_i32 m0, s57, 0xc000
	ds_read_b128 v[160:163], v218
	ds_read_b128 v[174:177], v218 offset:1024
	ds_read_b128 v[178:181], v218 offset:2048
	ds_read_b128 v[182:185], v218 offset:3072
	ds_read_b128 v[194:197], v218 offset:4096
	ds_read_b128 v[220:223], v218 offset:5120
	ds_read_b128 v[224:227], v218 offset:6144
	ds_read_b128 v[242:245], v218 offset:7168
	global_load_lds_dwordx4 v[186:187], off
	v_lshl_add_u64 v[186:187], s[36:37], 0, v[172:173]
	s_add_i32 m0, s57, 0xe000
	s_nop 0
	global_load_lds_dwordx4 v[186:187], off
	s_waitcnt vmcnt(8)
	s_waitcnt lgkmcnt(0)
	s_setprio 1
	s_barrier

; #define PG8_STAGE(bufoff, gbase, voff) do { _Pragma("unroll") for (int _i = 0; _i < 2; ++_i) \
;         __builtin_amdgcn_global_load_lds((const unsigned*)((const char*)(gbase) + (voff)[_i]), (PG8_LAS unsigned*)(lds + (bufoff) + ldsw + _i * 8192), 16, 0, 0); } while (0)
; #define PG8_LDA(dst, b, h) do { _Pragma("unroll") for (int m = 0; m < 4; ++m) _Pragma("unroll") for (int k = 0; k < 2; ++k) dst[m][k] = *(const PG8_LAS bf16x8*)(lds + PG8_SA(b, h) + aoff + m * 2048 + k * 1024); } while (0)
; #define PG8_MMA(ai, bj, At, Bt) do { __builtin_amdgcn_s_setprio(1); _Pragma("unroll") for (int m = 0; m < 4; ++m) _Pragma("unroll") for (int n = 0; n < 2; ++n) _Pragma("unroll") for (int k = 0; k < 2; ++k) \
;         acc[ai][bj][m][n] = __builtin_amdgcn_mfma_f32_16x16x32_bf16(Bt[n][k], At[m][k], acc[ai][bj][m][n], 0, 0, 0); __builtin_amdgcn_s_setprio(0); } while (0)
; #define PG8_WAIT_V(n) asm volatile("s_waitcnt vmcnt(" #n ")" ::: "memory")
; #define PG8_WAIT_L(n) asm volatile("s_waitcnt lgkmcnt(" #n ")" ::: "memory")
; #define PG8_BAR __builtin_amdgcn_s_barrier()
; #define PG8_SCHED __builtin_amdgcn_sched_barrier(0)
; template <class Epi, class Sched, bool ALIGN_EPI = false, bool SP2 = false>
; __device__ __forceinline__ void gemm_phase(PG8_LAS unsigned char* lds, const Gemm g, const Sched& S, const Epi& E) {
;     ...
;             PG8_WAIT_V(8); PG8_WAIT_L(0); PG8_BAR; PG8_MMA(0, 0, At, B0); PG8_MMA(0, 1, At, B1); PG8_BAR; PG8_SCHED;
;             PG8_LDA(At, 0, 1); PG8_STAGE(PG8_SB(0, 0), b2, voffB); PG8_STAGE(PG8_SB(0, 1), b2 + hstep, voffB); PG8_STAGE(PG8_SA(0, 0), a2, voffA);
;             PG8_WAIT_V(8); PG8_WAIT_L(0); PG8_BAR; PG8_MMA(1, 0, At, B0); PG8_MMA(1, 1, At, B1); PG8_BAR; PG8_SCHED;
	v_mfma_f32_16x16x32_bf16 v[156:159], v[56:59], v[160:163], v[156:159]
	v_mfma_f32_16x16x32_bf16 v[152:155], v[64:67], v[160:163], v[152:155]
	v_mfma_f32_16x16x32_bf16 v[140:143], v[56:59], v[178:181], v[140:143]
	v_mfma_f32_16x16x32_bf16 v[136:139], v[64:67], v[178:181], v[136:139]
	v_mfma_f32_16x16x32_bf16 v[124:127], v[56:59], v[194:197], v[124:127]
	v_mfma_f32_16x16x32_bf16 v[120:123], v[64:67], v[194:197], v[120:123]
	v_mfma_f32_16x16x32_bf16 v[108:111], v[56:59], v[224:227], v[108:111]
	v_mfma_f32_16x16x32_bf16 v[104:107], v[64:67], v[224:227], v[104:107]
	v_mfma_f32_16x16x32_bf16 v[156:159], v[60:63], v[174:177], v[156:159]
	v_mfma_f32_16x16x32_bf16 v[152:155], v[68:71], v[174:177], v[152:155]
	v_mfma_f32_16x16x32_bf16 v[140:143], v[60:63], v[182:185], v[140:143]
	v_mfma_f32_16x16x32_bf16 v[136:139], v[68:71], v[182:185], v[136:139]
	v_mfma_f32_16x16x32_bf16 v[124:127], v[60:63], v[220:223], v[124:127]
	v_mfma_f32_16x16x32_bf16 v[120:123], v[68:71], v[220:223], v[120:123]
	v_mfma_f32_16x16x32_bf16 v[108:111], v[60:63], v[242:245], v[108:111]
	v_mfma_f32_16x16x32_bf16 v[104:107], v[68:71], v[242:245], v[104:107]
	s_setprio 0
	s_setprio 1
	v_mfma_f32_16x16x32_bf16 v[148:151], v[76:79], v[160:163], v[148:151]
	v_mfma_f32_16x16x32_bf16 v[144:147], v[88:91], v[160:163], v[144:147]
	v_mfma_f32_16x16x32_bf16 v[132:135], v[76:79], v[178:181], v[132:135]
	v_mfma_f32_16x16x32_bf16 v[128:131], v[88:91], v[178:181], v[128:131]
	v_mfma_f32_16x16x32_bf16 v[116:119], v[76:79], v[194:197], v[116:119]
	v_mfma_f32_16x16x32_bf16 v[112:115], v[88:91], v[194:197], v[112:115]
	v_mfma_f32_16x16x32_bf16 v[100:103], v[76:79], v[224:227], v[100:103]
	v_mfma_f32_16x16x32_bf16 v[96:99], v[88:91], v[224:227], v[96:99]
	v_mfma_f32_16x16x32_bf16 v[148:151], v[80:83], v[174:177], v[148:151]
	v_mfma_f32_16x16x32_bf16 v[144:147], v[92:95], v[174:177], v[144:147]
	v_mfma_f32_16x16x32_bf16 v[132:135], v[80:83], v[182:185], v[132:135]
	v_mfma_f32_16x16x32_bf16 v[128:131], v[92:95], v[182:185], v[128:131]
	v_mfma_f32_16x16x32_bf16 v[116:119], v[80:83], v[220:223], v[116:119]
	v_mfma_f32_16x16x32_bf16 v[112:115], v[92:95], v[220:223], v[112:115]
	v_mfma_f32_16x16x32_bf16 v[100:103], v[80:83], v[242:245], v[100:103]
	v_mfma_f32_16x16x32_bf16 v[96:99], v[92:95], v[242:245], v[96:99]
	s_barrier
	s_setprio 0
	s_add_i32 s5, s5, s56
	v_lshl_add_u64 v[186:187], s[46:47], 0, v[188:189]
	s_mov_b32 m0, s5
	ds_read_b128 v[160:163], v218 offset:16384
	ds_read_b128 v[174:177], v218 offset:17408
	ds_read_b128 v[178:181], v218 offset:18432
	ds_read_b128 v[182:185], v218 offset:19456
	ds_read_b128 v[194:197], v218 offset:20480
	ds_read_b128 v[220:223], v218 offset:21504
	ds_read_b128 v[224:227], v218 offset:22528
	ds_read_b128 v[242:245], v218 offset:23552
	global_load_lds_dwordx4 v[186:187], off
	s_add_i32 m0, s5, 0x2000
	s_add_u32 s36, s46, 0xb0000
	v_lshl_add_u64 v[228:229], s[46:47], 0, v[164:165]
	s_addc_u32 s37, s47, 0
	s_add_i32 s5, s74, s56
	global_load_lds_dwordx4 v[228:229], off
	v_lshl_add_u64 v[238:239], s[36:37], 0, v[188:189]
	s_mov_b32 m0, s5
	v_lshl_add_u64 v[240:241], s[48:49], 0, v[166:167]
	global_load_lds_dwordx4 v[238:239], off
	v_lshl_add_u64 v[238:239], s[36:37], 0, v[164:165]
	s_add_i32 m0, s5, 0x2000
	s_nop 0
	global_load_lds_dwordx4 v[238:239], off
	v_lshl_add_u64 v[238:239], s[48:49], 0, v[168:169]
	s_mov_b32 m0, s57
	s_nop 0
	global_load_lds_dwordx4 v[238:239], off
	s_mov_b32 m0, s60
	s_nop 0
	global_load_lds_dwordx4 v[240:241], off
	s_waitcnt vmcnt(8)
	s_waitcnt lgkmcnt(0)
	s_setprio 1
	s_barrier

; #define PG8_STAGE(bufoff, gbase, voff) do { _Pragma("unroll") for (int _i = 0; _i < 2; ++_i) \
;         __builtin_amdgcn_global_load_lds((const unsigned*)((const char*)(gbase) + (voff)[_i]), (PG8_LAS unsigned*)(lds + (bufoff) + ldsw + _i * 8192), 16, 0, 0); } while (0)
; #define PG8_LDA(dst, b, h) do { _Pragma("unroll") for (int m = 0; m < 4; ++m) _Pragma("unroll") for (int k = 0; k < 2; ++k) dst[m][k] = *(const PG8_LAS bf16x8*)(lds + PG8_SA(b, h) + aoff + m * 2048 + k * 1024); } while (0)
; #define PG8_LDB(dst, b, h) do { _Pragma("unroll") for (int n = 0; n < 2; ++n) _Pragma("unroll") for (int k = 0; k < 2; ++k) dst[n][k] = *(const PG8_LAS bf16x8*)(lds + PG8_SB(b, h) + boff + n * 2048 + k * 1024); } while (0)
; #define PG8_MMA(ai, bj, At, Bt) do { __builtin_amdgcn_s_setprio(1); _Pragma("unroll") for (int m = 0; m < 4; ++m) _Pragma("unroll") for (int n = 0; n < 2; ++n) _Pragma("unroll") for (int k = 0; k < 2; ++k) \
;         acc[ai][bj][m][n] = __builtin_amdgcn_mfma_f32_16x16x32_bf16(Bt[n][k], At[m][k], acc[ai][bj][m][n], 0, 0, 0); __builtin_amdgcn_s_setprio(0); } while (0)
; #define PG8_WAIT_V(n) asm volatile("s_waitcnt vmcnt(" #n ")" ::: "memory")
; #define PG8_WAIT_L(n) asm volatile("s_waitcnt lgkmcnt(" #n ")" ::: "memory")
; #define PG8_BAR __builtin_amdgcn_s_barrier()
; #define PG8_SCHED __builtin_amdgcn_sched_barrier(0)
; template <class Epi, class Sched, bool ALIGN_EPI = false, bool SP2 = false>
; __device__ __forceinline__ void gemm_phase(PG8_LAS unsigned char* lds, const Gemm g, const Sched& S, const Epi& E) {
;     ...
;             PG8_WAIT_V(8); PG8_WAIT_L(0); PG8_BAR; PG8_MMA(1, 0, At, B0); PG8_MMA(1, 1, At, B1); PG8_BAR; PG8_SCHED;
;             PG8_LDB(B0, 1, 0); PG8_LDB(B1, 1, 1); PG8_SCHED; PG8_LDA(At, 1, 0); PG8_STAGE(PG8_SA(0, 1), a2 + hstep, voffA);
;             PG8_WAIT_V(8); PG8_WAIT_L(0); PG8_BAR; PG8_MMA(0, 0, At, B0); PG8_MMA(0, 1, At, B1); PG8_BAR; PG8_SCHED;
	v_mfma_f32_16x16x32_bf16 v[84:87], v[56:59], v[160:163], v[84:87]
	v_mfma_f32_16x16x32_bf16 v[72:75], v[64:67], v[160:163], v[72:75]
	v_mfma_f32_16x16x32_bf16 v[44:47], v[56:59], v[178:181], v[44:47]
	v_mfma_f32_16x16x32_bf16 v[40:43], v[64:67], v[178:181], v[40:43]
	v_mfma_f32_16x16x32_bf16 v[28:31], v[56:59], v[194:197], v[28:31]
	v_mfma_f32_16x16x32_bf16 v[24:27], v[64:67], v[194:197], v[24:27]
	v_mfma_f32_16x16x32_bf16 v[12:15], v[56:59], v[224:227], v[12:15]
	v_mfma_f32_16x16x32_bf16 v[8:11], v[64:67], v[224:227], v[8:11]
	v_mfma_f32_16x16x32_bf16 v[84:87], v[60:63], v[174:177], v[84:87]
	v_mfma_f32_16x16x32_bf16 v[72:75], v[68:71], v[174:177], v[72:75]
	v_mfma_f32_16x16x32_bf16 v[44:47], v[60:63], v[182:185], v[44:47]
	v_mfma_f32_16x16x32_bf16 v[40:43], v[68:71], v[182:185], v[40:43]
	v_mfma_f32_16x16x32_bf16 v[28:31], v[60:63], v[220:223], v[28:31]
	v_mfma_f32_16x16x32_bf16 v[24:27], v[68:71], v[220:223], v[24:27]
	v_mfma_f32_16x16x32_bf16 v[12:15], v[60:63], v[242:245], v[12:15]
	v_mfma_f32_16x16x32_bf16 v[8:11], v[68:71], v[242:245], v[8:11]
	s_setprio 0
	s_setprio 1
	v_mfma_f32_16x16x32_bf16 v[52:55], v[76:79], v[160:163], v[52:55]
	v_mfma_f32_16x16x32_bf16 v[48:51], v[88:91], v[160:163], v[48:51]
	v_mfma_f32_16x16x32_bf16 v[36:39], v[76:79], v[178:181], v[36:39]
	v_mfma_f32_16x16x32_bf16 v[32:35], v[88:91], v[178:181], v[32:35]
	v_mfma_f32_16x16x32_bf16 v[20:23], v[76:79], v[194:197], v[20:23]
	v_mfma_f32_16x16x32_bf16 v[16:19], v[88:91], v[194:197], v[16:19]
	v_mfma_f32_16x16x32_bf16 v[4:7], v[76:79], v[224:227], v[4:7]
	v_mfma_f32_16x16x32_bf16 v[0:3], v[88:91], v[224:227], v[0:3]
	v_mfma_f32_16x16x32_bf16 v[52:55], v[80:83], v[174:177], v[52:55]
	v_mfma_f32_16x16x32_bf16 v[48:51], v[92:95], v[174:177], v[48:51]
	v_mfma_f32_16x16x32_bf16 v[36:39], v[80:83], v[182:185], v[36:39]
	v_mfma_f32_16x16x32_bf16 v[32:35], v[92:95], v[182:185], v[32:35]
	v_mfma_f32_16x16x32_bf16 v[20:23], v[80:83], v[220:223], v[20:23]
	v_mfma_f32_16x16x32_bf16 v[16:19], v[92:95], v[220:223], v[16:19]
	v_mfma_f32_16x16x32_bf16 v[4:7], v[80:83], v[242:245], v[4:7]
	v_mfma_f32_16x16x32_bf16 v[0:3], v[92:95], v[242:245], v[0:3]
	s_barrier
	s_setprio 0
	s_add_i32 s5, 0, 0x18000
	s_add_i32 s74, 0, 0x1c000
	v_add_u32_e32 v68, s5, v199
	v_add_u32_e32 v92, s74, v199
	ds_read_b128 v[56:59], v68
	ds_read_b128 v[60:63], v68 offset:1024
	ds_read_b128 v[64:67], v68 offset:2048
	ds_read_b128 v[68:71], v68 offset:3072
	ds_read_b128 v[76:79], v92
	ds_read_b128 v[80:83], v92 offset:1024
	ds_read_b128 v[88:91], v92 offset:2048
	ds_read_b128 v[92:95], v92 offset:3072
	s_add_u32 s36, s48, 0xb0000
	s_addc_u32 s37, s49, 0
	s_mov_b32 m0, s61
	v_lshl_add_u64 v[246:247], s[36:37], 0, v[168:169]
	ds_read_b128 v[160:163], v218 offset:32768
	ds_read_b128 v[174:177], v218 offset:33792
	ds_read_b128 v[178:181], v218 offset:34816
	ds_read_b128 v[182:185], v218 offset:35840
	ds_read_b128 v[194:197], v218 offset:36864
	ds_read_b128 v[220:223], v218 offset:37888
	ds_read_b128 v[224:227], v218 offset:38912
	ds_read_b128 v[242:245], v218 offset:39936
	global_load_lds_dwordx4 v[246:247], off
	v_lshl_add_u64 v[246:247], s[36:37], 0, v[166:167]
	s_mov_b32 m0, s68
	s_nop 0
	global_load_lds_dwordx4 v[246:247], off
	s_waitcnt vmcnt(8)
	s_waitcnt lgkmcnt(0)
	s_setprio 1
	s_barrier

; #define PG8_STAGE(bufoff, gbase, voff) do { _Pragma("unroll") for (int _i = 0; _i < 2; ++_i) \
;         __builtin_amdgcn_global_load_lds((const unsigned*)((const char*)(gbase) + (voff)[_i]), (PG8_LAS unsigned*)(lds + (bufoff) + ldsw + _i * 8192), 16, 0, 0); } while (0)
; #define PG8_LDA(dst, b, h) do { _Pragma("unroll") for (int m = 0; m < 4; ++m) _Pragma("unroll") for (int k = 0; k < 2; ++k) dst[m][k] = *(const PG8_LAS bf16x8*)(lds + PG8_SA(b, h) + aoff + m * 2048 + k * 1024); } while (0)
; #define PG8_MMA(ai, bj, At, Bt) do { __builtin_amdgcn_s_setprio(1); _Pragma("unroll") for (int m = 0; m < 4; ++m) _Pragma("unroll") for (int n = 0; n < 2; ++n) _Pragma("unroll") for (int k = 0; k < 2; ++k) \
;         acc[ai][bj][m][n] = __builtin_amdgcn_mfma_f32_16x16x32_bf16(Bt[n][k], At[m][k], acc[ai][bj][m][n], 0, 0, 0); __builtin_amdgcn_s_setprio(0); } while (0)
; #define PG8_WAIT_V(n) asm volatile("s_waitcnt vmcnt(" #n ")" ::: "memory")
; #define PG8_WAIT_L(n) asm volatile("s_waitcnt lgkmcnt(" #n ")" ::: "memory")
; #define PG8_BAR __builtin_amdgcn_s_barrier()
; #define PG8_SCHED __builtin_amdgcn_sched_barrier(0)
; template <class Epi, class Sched, bool ALIGN_EPI = false, bool SP2 = false>
; __device__ __forceinline__ void gemm_phase(PG8_LAS unsigned char* lds, const Gemm g, const Sched& S, const Epi& E) {
;     ...
;             PG8_WAIT_V(8); PG8_WAIT_L(0); PG8_BAR; PG8_MMA(0, 0, At, B0); PG8_MMA(0, 1, At, B1); PG8_BAR; PG8_SCHED;
;             PG8_LDA(At, 1, 1); PG8_STAGE(PG8_SB(1, 0), b3, voffB); PG8_STAGE(PG8_SB(1, 1), b3 + hstep, voffB); PG8_STAGE(PG8_SA(1, 0), a3, voffA);
;             PG8_WAIT_V(8); PG8_WAIT_L(0); PG8_BAR; PG8_MMA(1, 0, At, B0); PG8_MMA(1, 1, At, B1); PG8_BAR; PG8_SCHED;
	v_mfma_f32_16x16x32_bf16 v[156:159], v[56:59], v[160:163], v[156:159]
	v_mfma_f32_16x16x32_bf16 v[152:155], v[64:67], v[160:163], v[152:155]
	v_mfma_f32_16x16x32_bf16 v[140:143], v[56:59], v[178:181], v[140:143]
	v_mfma_f32_16x16x32_bf16 v[136:139], v[64:67], v[178:181], v[136:139]
	v_mfma_f32_16x16x32_bf16 v[124:127], v[56:59], v[194:197], v[124:127]
	v_mfma_f32_16x16x32_bf16 v[120:123], v[64:67], v[194:197], v[120:123]
	v_mfma_f32_16x16x32_bf16 v[108:111], v[56:59], v[224:227], v[108:111]
	v_mfma_f32_16x16x32_bf16 v[104:107], v[64:67], v[224:227], v[104:107]
	v_mfma_f32_16x16x32_bf16 v[156:159], v[60:63], v[174:177], v[156:159]
	v_mfma_f32_16x16x32_bf16 v[152:155], v[68:71], v[174:177], v[152:155]
	v_mfma_f32_16x16x32_bf16 v[140:143], v[60:63], v[182:185], v[140:143]
	v_mfma_f32_16x16x32_bf16 v[136:139], v[68:71], v[182:185], v[136:139]
	v_mfma_f32_16x16x32_bf16 v[124:127], v[60:63], v[220:223], v[124:127]
	v_mfma_f32_16x16x32_bf16 v[120:123], v[68:71], v[220:223], v[120:123]
	v_mfma_f32_16x16x32_bf16 v[108:111], v[60:63], v[242:245], v[108:111]
	v_mfma_f32_16x16x32_bf16 v[104:107], v[68:71], v[242:245], v[104:107]
	s_setprio 0
	s_setprio 1
	v_mfma_f32_16x16x32_bf16 v[148:151], v[76:79], v[160:163], v[148:151]
	v_mfma_f32_16x16x32_bf16 v[144:147], v[88:91], v[160:163], v[144:147]
	v_mfma_f32_16x16x32_bf16 v[132:135], v[76:79], v[178:181], v[132:135]
	v_mfma_f32_16x16x32_bf16 v[128:131], v[88:91], v[178:181], v[128:131]
	v_mfma_f32_16x16x32_bf16 v[116:119], v[76:79], v[194:197], v[116:119]
	v_mfma_f32_16x16x32_bf16 v[112:115], v[88:91], v[194:197], v[112:115]
	v_mfma_f32_16x16x32_bf16 v[100:103], v[76:79], v[224:227], v[100:103]
	v_mfma_f32_16x16x32_bf16 v[96:99], v[88:91], v[224:227], v[96:99]
	v_mfma_f32_16x16x32_bf16 v[148:151], v[80:83], v[174:177], v[148:151]
	v_mfma_f32_16x16x32_bf16 v[144:147], v[92:95], v[174:177], v[144:147]
	v_mfma_f32_16x16x32_bf16 v[132:135], v[80:83], v[182:185], v[132:135]
	v_mfma_f32_16x16x32_bf16 v[128:131], v[92:95], v[182:185], v[128:131]
	v_mfma_f32_16x16x32_bf16 v[116:119], v[80:83], v[220:223], v[116:119]
	v_mfma_f32_16x16x32_bf16 v[112:115], v[92:95], v[220:223], v[112:115]
	v_mfma_f32_16x16x32_bf16 v[100:103], v[80:83], v[242:245], v[100:103]
	v_mfma_f32_16x16x32_bf16 v[96:99], v[92:95], v[242:245], v[96:99]
	s_barrier
	s_setprio 0
	s_add_i32 s5, s5, s56
	v_lshl_add_u64 v[186:187], v[186:187], 0, s[90:91]
	s_mov_b32 m0, s5
	ds_read_b128 v[160:163], v218 offset:49152
	ds_read_b128 v[174:177], v218 offset:50176
	ds_read_b128 v[178:181], v218 offset:51200
	ds_read_b128 v[182:185], v218 offset:52224
	ds_read_b128 v[194:197], v218 offset:53248
	ds_read_b128 v[220:223], v218 offset:54272
	ds_read_b128 v[224:227], v218 offset:55296
	ds_read_b128 v[242:245], v218 offset:56320
	global_load_lds_dwordx4 v[186:187], off
	s_add_i32 m0, s5, 0x2000
	s_add_u32 s36, s46, 0xb0080
	v_lshl_add_u64 v[186:187], v[228:229], 0, s[90:91]
	s_addc_u32 s37, s47, 0
	s_add_i32 s5, s74, s56
	global_load_lds_dwordx4 v[186:187], off
	v_lshl_add_u64 v[186:187], s[36:37], 0, v[188:189]
	s_mov_b32 m0, s5
	s_nop 0
	global_load_lds_dwordx4 v[186:187], off
	v_lshl_add_u64 v[186:187], s[36:37], 0, v[164:165]
	s_add_i32 m0, s5, 0x2000
	s_nop 0
	global_load_lds_dwordx4 v[186:187], off
	v_lshl_add_u64 v[186:187], v[238:239], 0, s[90:91]
	s_mov_b32 m0, s54
	s_nop 0
	global_load_lds_dwordx4 v[186:187], off
	v_lshl_add_u64 v[186:187], v[240:241], 0, s[90:91]
	s_mov_b32 m0, s55
	s_nop 0
	global_load_lds_dwordx4 v[186:187], off
	s_waitcnt vmcnt(8)
	s_waitcnt lgkmcnt(0)
	s_setprio 1
	s_barrier

; #define PG8_STAGE(bufoff, gbase, voff) do { _Pragma("unroll") for (int _i = 0; _i < 2; ++_i) \
;         __builtin_amdgcn_global_load_lds((const unsigned*)((const char*)(gbase) + (voff)[_i]), (PG8_LAS unsigned*)(lds + (bufoff) + ldsw + _i * 8192), 16, 0, 0); } while (0)
; #define PG8_LDA(dst, b, h) do { _Pragma("unroll") for (int m = 0; m < 4; ++m) _Pragma("unroll") for (int k = 0; k < 2; ++k) dst[m][k] = *(const PG8_LAS bf16x8*)(lds + PG8_SA(b, h) + aoff + m * 2048 + k * 1024); } while (0)
; #define PG8_LDB(dst, b, h) do { _Pragma("unroll") for (int n = 0; n < 2; ++n) _Pragma("unroll") for (int k = 0; k < 2; ++k) dst[n][k] = *(const PG8_LAS bf16x8*)(lds + PG8_SB(b, h) + boff + n * 2048 + k * 1024); } while (0)
; template <class Epi, class Sched, bool ALIGN_EPI = false, bool SP2 = false>
; __device__ __forceinline__ void gemm_phase(PG8_LAS unsigned char* lds, const Gemm g, const Sched& S, const Epi& E) {
;     ...
;             PG8_WAIT_V(8); PG8_WAIT_L(0); PG8_BAR; PG8_MMA(1, 0, At, B0); PG8_MMA(1, 1, At, B1); PG8_BAR; PG8_SCHED;
;             } else {
;             PG8_LDB(B0, 0, 0); PG8_SCHED; PG8_LDA(At, 0, 0); PG8_STAGE(PG8_SA(1, 1), a1 + hstep, voffA);
;             PG8_WAIT_L(8); PG8_BAR; PG8_WAIT_L(0); PG8_MMA(0, 0, At, B0); PG8_BAR; PG8_SCHED;
;             PG8_LDB(B1, 0, 1); PG8_STAGE(PG8_SB(0, 0), b2, voffB);
;             PG8_BAR; PG8_WAIT_L(0); PG8_MMA(0, 1, At, B1); PG8_BAR;
;             PG8_LDA(At, 0, 1); PG8_STAGE(PG8_SA(0, 0), a2, voffA);
;             PG8_BAR; PG8_WAIT_L(0); PG8_MMA(1, 0, At, B0); PG8_BAR; PG8_SCHED;
;             PG8_STAGE(PG8_SB(0, 1), b2 + hstep, voffB);
;             PG8_WAIT_V(6); PG8_BAR; PG8_MMA(1, 1, At, B1); PG8_BAR;
;             PG8_LDB(B0, 1, 0); PG8_SCHED; PG8_LDA(At, 1, 0); PG8_STAGE(PG8_SA(0, 1), a2 + hstep, voffA);
;             PG8_WAIT_L(8); PG8_BAR; PG8_WAIT_L(0); PG8_MMA(0, 0, At, B0); PG8_BAR; PG8_SCHED;
;             PG8_LDB(B1, 1, 1); PG8_STAGE(PG8_SB(1, 0), b3, voffB);
;             PG8_BAR; PG8_WAIT_L(0); PG8_MMA(0, 1, At, B1); PG8_BAR;
;             PG8_LDA(At, 1, 1); PG8_STAGE(PG8_SA(1, 0), a3, voffA);
;             PG8_BAR; PG8_WAIT_L(0); PG8_MMA(1, 0, At, B0); PG8_BAR; PG8_SCHED;
;             PG8_STAGE(PG8_SB(1, 1), b3 + hstep, voffB);
;             PG8_WAIT_V(6); PG8_BAR; PG8_MMA(1, 1, At, B1); PG8_BAR;
;             }
;         }
;         if constexpr (ALIGN_EPI) { if (wr == 0) PG8_BAR; }
	v_mfma_f32_16x16x32_bf16 v[84:87], v[56:59], v[160:163], v[84:87]
	v_mfma_f32_16x16x32_bf16 v[72:75], v[64:67], v[160:163], v[72:75]
	v_mfma_f32_16x16x32_bf16 v[44:47], v[56:59], v[178:181], v[44:47]
	v_mfma_f32_16x16x32_bf16 v[40:43], v[64:67], v[178:181], v[40:43]
	v_mfma_f32_16x16x32_bf16 v[28:31], v[56:59], v[194:197], v[28:31]
	v_mfma_f32_16x16x32_bf16 v[24:27], v[64:67], v[194:197], v[24:27]
	v_mfma_f32_16x16x32_bf16 v[12:15], v[56:59], v[224:227], v[12:15]
	v_mfma_f32_16x16x32_bf16 v[8:11], v[64:67], v[224:227], v[8:11]
	v_mfma_f32_16x16x32_bf16 v[84:87], v[60:63], v[174:177], v[84:87]
	v_mfma_f32_16x16x32_bf16 v[72:75], v[68:71], v[174:177], v[72:75]
	v_mfma_f32_16x16x32_bf16 v[44:47], v[60:63], v[182:185], v[44:47]
	v_mfma_f32_16x16x32_bf16 v[40:43], v[68:71], v[182:185], v[40:43]
	v_mfma_f32_16x16x32_bf16 v[28:31], v[60:63], v[220:223], v[28:31]
	v_mfma_f32_16x16x32_bf16 v[24:27], v[68:71], v[220:223], v[24:27]
	v_mfma_f32_16x16x32_bf16 v[12:15], v[60:63], v[242:245], v[12:15]
	v_mfma_f32_16x16x32_bf16 v[8:11], v[68:71], v[242:245], v[8:11]
	s_setprio 0
	s_setprio 1
	v_mfma_f32_16x16x32_bf16 v[52:55], v[76:79], v[160:163], v[52:55]
	v_mfma_f32_16x16x32_bf16 v[48:51], v[88:91], v[160:163], v[48:51]
	v_mfma_f32_16x16x32_bf16 v[36:39], v[76:79], v[178:181], v[36:39]
	v_mfma_f32_16x16x32_bf16 v[32:35], v[88:91], v[178:181], v[32:35]
	v_mfma_f32_16x16x32_bf16 v[20:23], v[76:79], v[194:197], v[20:23]
	v_mfma_f32_16x16x32_bf16 v[16:19], v[88:91], v[194:197], v[16:19]
	v_mfma_f32_16x16x32_bf16 v[4:7], v[76:79], v[224:227], v[4:7]
	v_mfma_f32_16x16x32_bf16 v[0:3], v[88:91], v[224:227], v[0:3]
	v_mfma_f32_16x16x32_bf16 v[52:55], v[80:83], v[174:177], v[52:55]
	v_mfma_f32_16x16x32_bf16 v[48:51], v[92:95], v[174:177], v[48:51]
	v_mfma_f32_16x16x32_bf16 v[36:39], v[80:83], v[182:185], v[36:39]
	v_mfma_f32_16x16x32_bf16 v[32:35], v[92:95], v[182:185], v[32:35]
	v_mfma_f32_16x16x32_bf16 v[20:23], v[80:83], v[220:223], v[20:23]
	v_mfma_f32_16x16x32_bf16 v[16:19], v[92:95], v[220:223], v[16:19]
	v_mfma_f32_16x16x32_bf16 v[4:7], v[80:83], v[242:245], v[4:7]
	v_mfma_f32_16x16x32_bf16 v[0:3], v[92:95], v[242:245], v[0:3]
	s_barrier
	s_setprio 0
	s_add_i32 s4, s4, 2
	s_add_u32 s0, s0, 0x100
	s_addc_u32 s1, s1, 0
	s_cmp_gt_u32 s4, 41
	s_mov_b64 s[36:37], s[38:39]
	s_cbranch_scc0 .LBB0_832
	s_and_b64 vcc, exec, s[24:25]
	s_cbranch_vccz .LBB0_835
	s_barrier
